# DMA issue interleaved one instruction per MFMA gap in H0 of the four main GEMM K-loops (m0 write and load split across gaps, no s_nop)
# speedup vs baseline: 1.0096x; 1.0096x over previous
; #define MFMA16(a, b, c) __builtin_amdgcn_mfma_f32_16x16x32_bf16((a), (b), (c), 0, 0, 0)
;     ...
;   for (int kt = 0; kt < nk; ++kt) {
;     const int buf = kt & 1;
;     const char* cA = smem + buf * STAGE + (wm * 32 * MI + r16) * 128;
;     const char* cB = smem + buf * STAGE + 32768 + (wn * 64 + r16) * 128;
; #pragma unroll
;     for (int k2 = 0; k2 < 2; ++k2) {
;       if (k2 == 1 && kt + 1 < nk) STAGE_TILE(buf ^ 1, (kt + 1) * 64)
;       const int po = ((4 * k2 + q4) ^ swz) * 16;
;       bf16x8 bf[4];
; #pragma unroll
;       for (int nt = 0; nt < 4; ++nt) bf[nt] = *(const bf16x8*)(cB + nt * 16 * 128 + po);
;       bf16x8 afc = *(const bf16x8*)(cA + po);
; #pragma unroll
;       for (int a = 0; a < MT; ++a) {
;         bf16x8 afn = afc;
;         if (a + 1 < MT) afn = *(const bf16x8*)(cA + (a + 1) * 16 * 128 + po);
;         __builtin_amdgcn_sched_barrier(0);
; #pragma unroll
;         for (int nt = 0; nt < 4; ++nt) acc[a][nt] = MFMA16(bf[nt], afc, acc[a][nt]);
;         __builtin_amdgcn_sched_barrier(0);
;         afc = afn;
;       }
;     }
;     asm volatile("s_waitcnt vmcnt(0)" ::: "memory");
;     __syncthreads();
;   }
.LBB0_48:
	s_and_b32 s42, s41, 0x10000
	s_add_i32 s43, s42, 0
	s_xor_b32 s42, s42, 0x10000
	v_add_u32_e32 v174, s43, v147
	v_add_u32_e32 v162, v174, v146
	v_add_u32_e32 v149, s43, v148
	ds_read_b128 v[150:153], v162 offset:32768
	ds_read_b128 v[154:157], v162 offset:34816
	ds_read_b128 v[158:161], v162 offset:36864
	ds_read_b128 v[162:165], v162 offset:38912
	v_add_u32_e32 v175, v149, v146
	ds_read_b128 v[166:169], v175
	ds_read_b128 v[170:173], v175 offset:2048
	s_waitcnt lgkmcnt(1)
	v_mfma_f32_16x16x32_bf16 v[126:129], v[150:153], v[166:169], v[126:129]
	v_readfirstlane_b32 s43, v145
	v_mfma_f32_16x16x32_bf16 v[122:125], v[154:157], v[166:169], v[122:125]
	s_nop 0
	v_mfma_f32_16x16x32_bf16 v[118:121], v[158:161], v[166:169], v[118:121]
	s_add_u32 s43, s43, s42
	v_mfma_f32_16x16x32_bf16 v[114:117], v[162:165], v[166:169], v[114:117]
	ds_read_b128 v[166:169], v175 offset:4096
	s_waitcnt lgkmcnt(1)
	v_mfma_f32_16x16x32_bf16 v[110:113], v[150:153], v[170:173], v[110:113]
	s_add_u32 m0, s43, 0x0
	v_mfma_f32_16x16x32_bf16 v[106:109], v[154:157], v[170:173], v[106:109]
	global_load_lds_dwordx4 v176, s[100:101]
	v_mfma_f32_16x16x32_bf16 v[102:105], v[158:161], v[170:173], v[102:105]
	s_add_u32 m0, s43, 0x2000
	v_mfma_f32_16x16x32_bf16 v[98:101], v[162:165], v[170:173], v[98:101]
	ds_read_b128 v[170:173], v175 offset:6144
	s_waitcnt lgkmcnt(1)
	v_mfma_f32_16x16x32_bf16 v[94:97], v[150:153], v[166:169], v[94:97]
	global_load_lds_dwordx4 v177, s[100:101]
	v_mfma_f32_16x16x32_bf16 v[90:93], v[154:157], v[166:169], v[90:93]
	s_add_u32 m0, s43, 0x4000
	v_mfma_f32_16x16x32_bf16 v[86:89], v[158:161], v[166:169], v[86:89]
	global_load_lds_dwordx4 v178, s[100:101]
	v_mfma_f32_16x16x32_bf16 v[82:85], v[162:165], v[166:169], v[82:85]
	ds_read_b128 v[166:169], v175 offset:8192
	s_waitcnt lgkmcnt(1)
	v_mfma_f32_16x16x32_bf16 v[78:81], v[150:153], v[170:173], v[78:81]
	s_add_u32 m0, s43, 0x6000
	v_mfma_f32_16x16x32_bf16 v[74:77], v[154:157], v[170:173], v[74:77]
	global_load_lds_dwordx4 v179, s[100:101]
	v_mfma_f32_16x16x32_bf16 v[70:73], v[158:161], v[170:173], v[70:73]
	s_add_u32 m0, s43, 0x8000
	v_mfma_f32_16x16x32_bf16 v[66:69], v[162:165], v[170:173], v[66:69]
	ds_read_b128 v[170:173], v175 offset:10240
	s_waitcnt lgkmcnt(1)
	v_mfma_f32_16x16x32_bf16 v[62:65], v[150:153], v[166:169], v[62:65]
	global_load_lds_dwordx4 v180, s[100:101]
	v_mfma_f32_16x16x32_bf16 v[58:61], v[154:157], v[166:169], v[58:61]
	s_add_u32 m0, s43, 0xa000
	v_mfma_f32_16x16x32_bf16 v[54:57], v[158:161], v[166:169], v[54:57]
	global_load_lds_dwordx4 v181, s[100:101]
	v_mfma_f32_16x16x32_bf16 v[50:53], v[162:165], v[166:169], v[50:53]
	ds_read_b128 v[166:169], v175 offset:12288
	s_waitcnt lgkmcnt(1)
	v_mfma_f32_16x16x32_bf16 v[46:49], v[150:153], v[170:173], v[46:49]
	s_add_u32 m0, s43, 0xc000
	v_mfma_f32_16x16x32_bf16 v[42:45], v[154:157], v[170:173], v[42:45]
	global_load_lds_dwordx4 v182, s[100:101]
	v_mfma_f32_16x16x32_bf16 v[38:41], v[158:161], v[170:173], v[38:41]
	s_add_u32 m0, s43, 0xe000
	v_mfma_f32_16x16x32_bf16 v[34:37], v[162:165], v[170:173], v[34:37]
	ds_read_b128 v[170:173], v175 offset:14336
	s_waitcnt lgkmcnt(1)
	v_mfma_f32_16x16x32_bf16 v[30:33], v[150:153], v[166:169], v[30:33]
	global_load_lds_dwordx4 v183, s[100:101]
	v_mfma_f32_16x16x32_bf16 v[26:29], v[154:157], v[166:169], v[26:29]
	v_mfma_f32_16x16x32_bf16 v[22:25], v[158:161], v[166:169], v[22:25]
	v_mfma_f32_16x16x32_bf16 v[18:21], v[162:165], v[166:169], v[18:21]
	s_waitcnt lgkmcnt(0)
	v_mfma_f32_16x16x32_bf16 v[14:17], v[150:153], v[170:173], v[14:17]
	v_mfma_f32_16x16x32_bf16 v[10:13], v[154:157], v[170:173], v[10:13]
	v_mfma_f32_16x16x32_bf16 v[6:9], v[158:161], v[170:173], v[6:9]
	v_mfma_f32_16x16x32_bf16 v[2:5], v[162:165], v[170:173], v[2:5]
	v_add_u32_e32 v162, v174, v144
	ds_read_b128 v[150:153], v162 offset:32768
	ds_read_b128 v[154:157], v162 offset:34816
	ds_read_b128 v[158:161], v162 offset:36864
	ds_read_b128 v[162:165], v162 offset:38912
	v_add_u32_e32 v149, v149, v144
	ds_read_b128 v[166:169], v149
	ds_read_b128 v[170:173], v149 offset:2048
	s_waitcnt lgkmcnt(0)
	v_mfma_f32_16x16x32_bf16 v[126:129], v[150:153], v[166:169], v[126:129]
	v_mfma_f32_16x16x32_bf16 v[122:125], v[154:157], v[166:169], v[122:125]
	v_mfma_f32_16x16x32_bf16 v[118:121], v[158:161], v[166:169], v[118:121]
	v_mfma_f32_16x16x32_bf16 v[114:117], v[162:165], v[166:169], v[114:117]
	ds_read_b128 v[166:169], v149 offset:4096
	v_mfma_f32_16x16x32_bf16 v[110:113], v[150:153], v[170:173], v[110:113]
	v_mfma_f32_16x16x32_bf16 v[106:109], v[154:157], v[170:173], v[106:109]
	v_mfma_f32_16x16x32_bf16 v[102:105], v[158:161], v[170:173], v[102:105]
	v_mfma_f32_16x16x32_bf16 v[98:101], v[162:165], v[170:173], v[98:101]
	ds_read_b128 v[170:173], v149 offset:6144
	s_waitcnt lgkmcnt(0)
	v_mfma_f32_16x16x32_bf16 v[94:97], v[150:153], v[166:169], v[94:97]
	v_mfma_f32_16x16x32_bf16 v[90:93], v[154:157], v[166:169], v[90:93]
	v_mfma_f32_16x16x32_bf16 v[86:89], v[158:161], v[166:169], v[86:89]
	v_mfma_f32_16x16x32_bf16 v[82:85], v[162:165], v[166:169], v[82:85]
	ds_read_b128 v[166:169], v149 offset:8192
	v_mfma_f32_16x16x32_bf16 v[78:81], v[150:153], v[170:173], v[78:81]
	v_mfma_f32_16x16x32_bf16 v[74:77], v[154:157], v[170:173], v[74:77]
	v_mfma_f32_16x16x32_bf16 v[70:73], v[158:161], v[170:173], v[70:73]
	v_mfma_f32_16x16x32_bf16 v[66:69], v[162:165], v[170:173], v[66:69]
	ds_read_b128 v[170:173], v149 offset:10240
	s_waitcnt lgkmcnt(0)
	v_mfma_f32_16x16x32_bf16 v[62:65], v[150:153], v[166:169], v[62:65]
	v_mfma_f32_16x16x32_bf16 v[58:61], v[154:157], v[166:169], v[58:61]
	v_mfma_f32_16x16x32_bf16 v[54:57], v[158:161], v[166:169], v[54:57]
	v_mfma_f32_16x16x32_bf16 v[50:53], v[162:165], v[166:169], v[50:53]
	ds_read_b128 v[166:169], v149 offset:12288
	v_mfma_f32_16x16x32_bf16 v[46:49], v[150:153], v[170:173], v[46:49]
	v_mfma_f32_16x16x32_bf16 v[42:45], v[154:157], v[170:173], v[42:45]
	v_mfma_f32_16x16x32_bf16 v[38:41], v[158:161], v[170:173], v[38:41]
	v_mfma_f32_16x16x32_bf16 v[34:37], v[162:165], v[170:173], v[34:37]
	ds_read_b128 v[170:173], v149 offset:14336
	s_waitcnt lgkmcnt(0)
	v_mfma_f32_16x16x32_bf16 v[30:33], v[150:153], v[166:169], v[30:33]
	v_mfma_f32_16x16x32_bf16 v[26:29], v[154:157], v[166:169], v[26:29]
	v_mfma_f32_16x16x32_bf16 v[22:25], v[158:161], v[166:169], v[22:25]
	v_mfma_f32_16x16x32_bf16 v[18:21], v[162:165], v[166:169], v[18:21]
	v_mfma_f32_16x16x32_bf16 v[14:17], v[150:153], v[170:173], v[14:17]
	v_mfma_f32_16x16x32_bf16 v[10:13], v[154:157], v[170:173], v[10:13]
	v_mfma_f32_16x16x32_bf16 v[6:9], v[158:161], v[170:173], v[6:9]
	v_mfma_f32_16x16x32_bf16 v[2:5], v[162:165], v[170:173], v[2:5]
	s_waitcnt vmcnt(0)
	s_add_u32 s100, s100, 0x80
	s_addc_u32 s101, s101, 0
	s_add_u32 s16, s16, 0x80
	s_addc_u32 s17, s17, 0
	s_add_i32 s41, s41, 0x10000
	s_cmpk_eq_i32 s16, 0x1580
	s_waitcnt vmcnt(0)
	s_barrier
; #define MFMA16(a, b, c) __builtin_amdgcn_mfma_f32_16x16x32_bf16((a), (b), (c), 0, 0, 0)
;     ...
;   for (int kt = 0; kt < nk; ++kt) {
;     const int buf = kt & 1;
;     const char* cA = smem + buf * STAGE + (wm * 32 * MI + r16) * 128;
;     const char* cB = smem + buf * STAGE + 32768 + (wn * 64 + r16) * 128;
; #pragma unroll
;     for (int k2 = 0; k2 < 2; ++k2) {
;       if (k2 == 1 && kt + 1 < nk) STAGE_TILE(buf ^ 1, (kt + 1) * 64)
;       const int po = ((4 * k2 + q4) ^ swz) * 16;
;       bf16x8 bf[4];
; #pragma unroll
;       for (int nt = 0; nt < 4; ++nt) bf[nt] = *(const bf16x8*)(cB + nt * 16 * 128 + po);
;       bf16x8 afc = *(const bf16x8*)(cA + po);
; #pragma unroll
;       for (int a = 0; a < MT; ++a) {
;         bf16x8 afn = afc;
;         if (a + 1 < MT) afn = *(const bf16x8*)(cA + (a + 1) * 16 * 128 + po);
;         __builtin_amdgcn_sched_barrier(0);
; #pragma unroll
;         for (int nt = 0; nt < 4; ++nt) acc[a][nt] = MFMA16(bf[nt], afc, acc[a][nt]);
;         __builtin_amdgcn_sched_barrier(0);
;         afc = afn;
;       }
;     }
	s_cbranch_scc0 .LBB0_48
	s_add_i32 s16, 0, 0x10000
	v_add_u32_e32 v138, s16, v148
	v_readlane_b32 s16, v254, 18
	s_nop 1
	v_add_u32_e32 v139, s16, v147
	v_add_u32_e32 v145, v139, v146
	ds_read_b128 v[130:133], v145
	ds_read_b128 v[134:137], v145 offset:2048
	ds_read_b128 v[148:151], v145 offset:4096
	ds_read_b128 v[152:155], v145 offset:6144
	v_add_u32_e32 v145, v138, v146
	ds_read_b128 v[156:159], v145
	ds_read_b128 v[160:163], v145 offset:2048
	s_waitcnt lgkmcnt(1)
	v_mfma_f32_16x16x32_bf16 v[126:129], v[130:133], v[156:159], v[126:129]
	v_mfma_f32_16x16x32_bf16 v[122:125], v[134:137], v[156:159], v[122:125]
	v_mfma_f32_16x16x32_bf16 v[118:121], v[148:151], v[156:159], v[118:121]
	v_mfma_f32_16x16x32_bf16 v[114:117], v[152:155], v[156:159], v[114:117]
	ds_read_b128 v[156:159], v145 offset:4096
	s_waitcnt lgkmcnt(1)
	v_mfma_f32_16x16x32_bf16 v[110:113], v[130:133], v[160:163], v[110:113]
	v_mfma_f32_16x16x32_bf16 v[106:109], v[134:137], v[160:163], v[106:109]
	v_mfma_f32_16x16x32_bf16 v[102:105], v[148:151], v[160:163], v[102:105]
	v_mfma_f32_16x16x32_bf16 v[98:101], v[152:155], v[160:163], v[98:101]
	ds_read_b128 v[160:163], v145 offset:6144
	s_waitcnt lgkmcnt(1)
	v_mfma_f32_16x16x32_bf16 v[94:97], v[130:133], v[156:159], v[94:97]
	v_mfma_f32_16x16x32_bf16 v[90:93], v[134:137], v[156:159], v[90:93]
	v_mfma_f32_16x16x32_bf16 v[86:89], v[148:151], v[156:159], v[86:89]
	v_mfma_f32_16x16x32_bf16 v[82:85], v[152:155], v[156:159], v[82:85]
	ds_read_b128 v[156:159], v145 offset:8192
	s_waitcnt lgkmcnt(1)
	v_mfma_f32_16x16x32_bf16 v[78:81], v[130:133], v[160:163], v[78:81]
	v_mfma_f32_16x16x32_bf16 v[74:77], v[134:137], v[160:163], v[74:77]
	v_mfma_f32_16x16x32_bf16 v[70:73], v[148:151], v[160:163], v[70:73]
	v_mfma_f32_16x16x32_bf16 v[66:69], v[152:155], v[160:163], v[66:69]
	ds_read_b128 v[160:163], v145 offset:10240
	s_waitcnt lgkmcnt(1)
	v_mfma_f32_16x16x32_bf16 v[62:65], v[130:133], v[156:159], v[62:65]
	v_mfma_f32_16x16x32_bf16 v[58:61], v[134:137], v[156:159], v[58:61]
	v_mfma_f32_16x16x32_bf16 v[54:57], v[148:151], v[156:159], v[54:57]
	v_mfma_f32_16x16x32_bf16 v[50:53], v[152:155], v[156:159], v[50:53]
	ds_read_b128 v[156:159], v145 offset:12288
	s_waitcnt lgkmcnt(1)
	v_mfma_f32_16x16x32_bf16 v[46:49], v[130:133], v[160:163], v[46:49]
	v_mfma_f32_16x16x32_bf16 v[42:45], v[134:137], v[160:163], v[42:45]
	v_mfma_f32_16x16x32_bf16 v[38:41], v[148:151], v[160:163], v[38:41]
	v_mfma_f32_16x16x32_bf16 v[34:37], v[152:155], v[160:163], v[34:37]
	ds_read_b128 v[160:163], v145 offset:14336
	s_waitcnt lgkmcnt(1)
	v_mfma_f32_16x16x32_bf16 v[30:33], v[130:133], v[156:159], v[30:33]
	v_mfma_f32_16x16x32_bf16 v[26:29], v[134:137], v[156:159], v[26:29]
	v_mfma_f32_16x16x32_bf16 v[22:25], v[148:151], v[156:159], v[22:25]
	v_mfma_f32_16x16x32_bf16 v[18:21], v[152:155], v[156:159], v[18:21]
	s_waitcnt lgkmcnt(0)
	v_mfma_f32_16x16x32_bf16 v[14:17], v[130:133], v[160:163], v[14:17]
	v_mfma_f32_16x16x32_bf16 v[10:13], v[134:137], v[160:163], v[10:13]
	v_mfma_f32_16x16x32_bf16 v[6:9], v[148:151], v[160:163], v[6:9]
	v_mfma_f32_16x16x32_bf16 v[2:5], v[152:155], v[160:163], v[2:5]
	v_add_u32_e32 v139, v139, v144
	ds_read_b128 v[130:133], v139
	ds_read_b128 v[134:137], v139 offset:2048
	ds_read_b128 v[146:149], v139 offset:4096
	ds_read_b128 v[150:153], v139 offset:6144
	v_add_u32_e32 v138, v138, v144
	ds_read_b128 v[154:157], v138
	ds_read_b128 v[158:161], v138 offset:2048
	s_waitcnt lgkmcnt(1)
	v_mfma_f32_16x16x32_bf16 v[126:129], v[130:133], v[154:157], v[126:129]
	v_mfma_f32_16x16x32_bf16 v[122:125], v[134:137], v[154:157], v[122:125]
	v_mfma_f32_16x16x32_bf16 v[118:121], v[146:149], v[154:157], v[118:121]
	v_mfma_f32_16x16x32_bf16 v[114:117], v[150:153], v[154:157], v[114:117]
	ds_read_b128 v[154:157], v138 offset:4096
	s_waitcnt lgkmcnt(1)
	v_mfma_f32_16x16x32_bf16 v[110:113], v[130:133], v[158:161], v[110:113]
	v_mfma_f32_16x16x32_bf16 v[106:109], v[134:137], v[158:161], v[106:109]
	v_mfma_f32_16x16x32_bf16 v[102:105], v[146:149], v[158:161], v[102:105]
	v_mfma_f32_16x16x32_bf16 v[98:101], v[150:153], v[158:161], v[98:101]
	ds_read_b128 v[158:161], v138 offset:6144
	s_waitcnt lgkmcnt(1)
	v_mfma_f32_16x16x32_bf16 v[94:97], v[130:133], v[154:157], v[94:97]
	v_mfma_f32_16x16x32_bf16 v[90:93], v[134:137], v[154:157], v[90:93]
	v_mfma_f32_16x16x32_bf16 v[86:89], v[146:149], v[154:157], v[86:89]
	v_mfma_f32_16x16x32_bf16 v[82:85], v[150:153], v[154:157], v[82:85]
	ds_read_b128 v[154:157], v138 offset:8192
	s_waitcnt lgkmcnt(1)
	v_mfma_f32_16x16x32_bf16 v[78:81], v[130:133], v[158:161], v[78:81]
	v_mfma_f32_16x16x32_bf16 v[74:77], v[134:137], v[158:161], v[74:77]
	v_mfma_f32_16x16x32_bf16 v[70:73], v[146:149], v[158:161], v[70:73]
	v_mfma_f32_16x16x32_bf16 v[66:69], v[150:153], v[158:161], v[66:69]
	ds_read_b128 v[158:161], v138 offset:10240
	s_waitcnt lgkmcnt(1)
	v_mfma_f32_16x16x32_bf16 v[62:65], v[130:133], v[154:157], v[62:65]
	v_mfma_f32_16x16x32_bf16 v[58:61], v[134:137], v[154:157], v[58:61]
	v_mfma_f32_16x16x32_bf16 v[54:57], v[146:149], v[154:157], v[54:57]
	v_mfma_f32_16x16x32_bf16 v[50:53], v[150:153], v[154:157], v[50:53]
	ds_read_b128 v[154:157], v138 offset:12288
	s_waitcnt lgkmcnt(1)
	v_mfma_f32_16x16x32_bf16 v[46:49], v[130:133], v[158:161], v[46:49]
	v_mfma_f32_16x16x32_bf16 v[42:45], v[134:137], v[158:161], v[42:45]
	v_mfma_f32_16x16x32_bf16 v[38:41], v[146:149], v[158:161], v[38:41]
	v_mfma_f32_16x16x32_bf16 v[34:37], v[150:153], v[158:161], v[34:37]
	ds_read_b128 v[158:161], v138 offset:14336
	s_waitcnt lgkmcnt(1)
;     ...
;     for (int a = 0; a < MT; ++a) ep(row0 + 16 * a, cbw, q4, acc[a][0], acc[a][1], acc[a][2], acc[a][3]);
;   } else {
; #pragma unroll
;     for (int a = 0; a < MT; ++a)
; #pragma unroll
;       for (int nt = 0; nt < 4; ++nt)
;         ep(row0 + 16 * a, cbw + 16 * nt + 4 * q4, acc[a][nt][0], acc[a][nt][1], acc[a][nt][2], acc[a][nt][3]);
; DI void phase_resid(char* smem, const Params& p, int layer, const bf16_t* A, int K, const bf16_t* W, int gate_idx, bool first) {
;     ...
;   auto ep = [&](int row, int col, float v0, float v1, float v2, float v3) {
;     const int b = row / TT, t = row - b * TT;
;     const float4 g = *(const float4*)(p.mod + (size_t)(layer * 5 + (t < CTXL ? 4 : b)) * 6144 + gate_idx * 1024 + col);
;     const float4 xo = *(const float4*)(xsrc_row(p, first, row) + col);
;     *(float4*)(xdst_row(p, row) + col) = make_float4(xo.x + g.x * v0, xo.y + g.y * v1, xo.z + g.z * v2, xo.w + g.w * v3);
;   };
	v_mfma_f32_16x16x32_bf16 v[30:33], v[130:133], v[154:157], v[30:33]
	v_mfma_f32_16x16x32_bf16 v[26:29], v[134:137], v[154:157], v[26:29]
	v_mfma_f32_16x16x32_bf16 v[22:25], v[146:149], v[154:157], v[22:25]
	v_mfma_f32_16x16x32_bf16 v[18:21], v[150:153], v[154:157], v[18:21]
	s_waitcnt lgkmcnt(0)
	v_mfma_f32_16x16x32_bf16 v[14:17], v[130:133], v[158:161], v[14:17]
	v_mfma_f32_16x16x32_bf16 v[10:13], v[134:137], v[158:161], v[10:13]
	v_mfma_f32_16x16x32_bf16 v[6:9], v[146:149], v[158:161], v[6:9]
	v_mfma_f32_16x16x32_bf16 v[2:5], v[150:153], v[158:161], v[2:5]
	v_or_b32_e32 v131, s40, v142
	v_lshlrev_b32_e32 v130, 6, v143
	v_lshl_add_u32 v142, v140, 7, v131
	v_lshlrev_b32_e32 v131, 2, v141
	v_or3_b32 v134, v130, v131, s39
	v_mul_hi_i32 v130, v142, s1
	v_lshrrev_b32_e32 v131, 31, v130
	v_ashrrev_i32_e32 v130, 11, v130
	v_add_u32_e32 v130, v130, v131
	v_mad_i32_i24 v131, v130, s90, v142
	s_movk_i32 s39, 0x100
	v_cmp_gt_i32_e32 vcc, s39, v131
	v_add_u32_e32 v132, 0xffffff00, v131
	v_ashrrev_i32_e32 v133, 31, v131
	v_readlane_b32 s40, v254, 1
	v_cndmask_b32_e64 v135, v130, 4, vcc
	v_cndmask_b32_e32 v133, 0, v133, vcc
	v_cndmask_b32_e32 v132, v132, v131, vcc
	v_ashrrev_i32_e32 v131, 31, v130
	v_cndmask_b32_e64 v136, 25, 20, vcc
	v_readlane_b32 s41, v254, 2
	v_lshlrev_b64 v[140:141], v136, v[130:131]
	v_lshlrev_b64 v[150:151], 12, v[132:133]
	v_add_u32_e32 v130, s37, v135
	v_mov_b64_e32 v[132:133], s[40:41]
	s_movk_i32 s40, 0x6000
	v_readlane_b32 s42, v254, 3
	v_readlane_b32 s43, v254, 4
	v_mad_i64_i32 v[130:131], s[16:17], v130, s40, v[132:133]
	s_mov_b64 s[42:43], 0x5000
	v_ashrrev_i32_e32 v135, 31, v134
	v_readlane_b32 s16, v252, 26
	v_lshl_add_u64 v[136:137], v[130:131], 0, s[42:43]
	v_lshlrev_b64 v[130:131], 2, v[134:135]
	v_mov_b32_e32 v135, s16
	v_readlane_b32 s16, v252, 28
	s_waitcnt vmcnt(0)
	s_barrier
	s_nop 0
	v_mov_b32_e32 v143, s16
	v_readlane_b32 s16, v252, 25
	v_cndmask_b32_e32 v139, v135, v143, vcc
	s_nop 0
	v_mov_b32_e32 v144, s16
	v_readlane_b32 s16, v252, 27
	v_readlane_b32 s68, v252, 5
	v_readlane_b32 s80, v252, 17
	v_mov_b32_e32 v145, s16
	v_cndmask_b32_e32 v138, v144, v145, vcc
	global_load_dwordx2 v[138:139], v[138:139], off
	v_readlane_b32 s81, v252, 18
	v_readlane_b32 s82, v252, 19
	v_readlane_b32 s83, v252, 20
	v_mov_b32_e32 v146, s81
	v_mov_b32_e32 v148, s80
	v_mov_b32_e32 v147, s83
	v_mov_b32_e32 v149, s82
	v_cndmask_b32_e32 v155, v146, v147, vcc
	v_cndmask_b32_e32 v154, v148, v149, vcc
	v_lshl_add_u64 v[152:153], v[136:137], 0, v[130:131]
	s_add_i32 s38, s38, s30
	s_cmp_gt_i32 s38, 31
	v_readlane_b32 s44, v254, 5
	v_readlane_b32 s45, v254, 6
	v_readlane_b32 s46, v254, 7
	v_readlane_b32 s47, v254, 8
	v_readlane_b32 s48, v254, 9
	v_readlane_b32 s49, v254, 10
	v_readlane_b32 s50, v254, 11
	v_readlane_b32 s51, v254, 12
	v_readlane_b32 s52, v254, 13
	v_readlane_b32 s53, v254, 14
	v_readlane_b32 s54, v254, 15
	v_readlane_b32 s55, v254, 16
	v_readlane_b32 s69, v252, 6
	v_readlane_b32 s70, v252, 7
	v_readlane_b32 s71, v252, 8
	v_readlane_b32 s72, v252, 9
	v_readlane_b32 s73, v252, 10
	v_readlane_b32 s74, v252, 11
	v_readlane_b32 s75, v252, 12
	v_readlane_b32 s76, v252, 13
	v_readlane_b32 s77, v252, 14
	v_readlane_b32 s78, v252, 15
	v_readlane_b32 s79, v252, 16
	s_waitcnt vmcnt(0)
	v_lshl_add_u64 v[138:139], v[138:139], 0, v[140:141]
	v_lshl_add_u64 v[138:139], v[138:139], 0, v[150:151]
	v_lshl_add_u64 v[140:141], v[154:155], 0, v[140:141]
	v_lshl_add_u64 v[138:139], v[138:139], 0, v[130:131]
	v_lshl_add_u64 v[140:141], v[140:141], 0, v[150:151]
	v_lshl_add_u64 v[140:141], v[140:141], 0, v[130:131]
	s_cselect_b64 s[16:17], -1, 0
	global_load_dwordx4 v[156:159], v[152:153], off
	global_load_dwordx4 v[160:163], v[152:153], off offset:64
	global_load_dwordx4 v[164:167], v[152:153], off offset:128
	global_load_dwordx4 v[168:171], v[152:153], off offset:192
	global_load_dwordx4 v[172:175], v[138:139], off
	global_load_dwordx4 v[176:179], v[138:139], off offset:64
	global_load_dwordx4 v[180:183], v[138:139], off offset:128
	global_load_dwordx4 v[184:187], v[138:139], off offset:192
	v_add_co_u32_e32 v138, vcc, 0x10000, v138
	s_nop 1
	v_addc_co_u32_e32 v139, vcc, 0, v139, vcc
	global_load_dwordx4 v[198:201], v[138:139], off
	global_load_dwordx4 v[202:205], v[138:139], off offset:64
	global_load_dwordx4 v[206:209], v[138:139], off offset:128
	global_load_dwordx4 v[210:213], v[138:139], off offset:192
	v_add_co_u32_e32 v138, vcc, 0x10000, v138
	s_nop 1
	v_addc_co_u32_e32 v139, vcc, 0, v139, vcc
	global_load_dwordx4 v[214:217], v[138:139], off
	global_load_dwordx4 v[218:221], v[138:139], off offset:64
	global_load_dwordx4 v[222:225], v[138:139], off offset:128
	global_load_dwordx4 v[142:145], v[138:139], off offset:192
	v_add_co_u32_e32 v138, vcc, 0x10000, v138
	s_nop 1
	v_addc_co_u32_e32 v139, vcc, 0, v139, vcc
	s_waitcnt vmcnt(8)
	v_pk_fma_f32 v[126:127], v[126:127], v[156:157], v[172:173]
	v_pk_fma_f32 v[128:129], v[128:129], v[158:159], v[174:175]
	v_pk_fma_f32 v[122:123], v[122:123], v[160:161], v[176:177]
	v_pk_fma_f32 v[124:125], v[124:125], v[162:163], v[178:179]
	v_pk_fma_f32 v[118:119], v[118:119], v[164:165], v[180:181]
	v_pk_fma_f32 v[120:121], v[120:121], v[166:167], v[182:183]
	v_pk_fma_f32 v[114:115], v[114:115], v[168:169], v[184:185]
	v_pk_fma_f32 v[116:117], v[116:117], v[170:171], v[186:187]
	global_store_dwordx4 v[140:141], v[126:129], off
	global_store_dwordx4 v[140:141], v[122:125], off offset:64
	global_store_dwordx4 v[140:141], v[118:121], off offset:128
	global_store_dwordx4 v[140:141], v[114:117], off offset:192
	v_add_co_u32_e32 v140, vcc, 0x10000, v140
	s_nop 1
	v_addc_co_u32_e32 v141, vcc, 0, v141, vcc
	global_load_dwordx4 v[172:175], v[138:139], off
	global_load_dwordx4 v[176:179], v[138:139], off offset:64
	global_load_dwordx4 v[180:183], v[138:139], off offset:128
	global_load_dwordx4 v[184:187], v[138:139], off offset:192
	v_add_co_u32_e32 v138, vcc, 0x10000, v138
	s_nop 1
	v_addc_co_u32_e32 v139, vcc, 0, v139, vcc
	s_waitcnt vmcnt(12)
;     ...
; #pragma unroll
;     for (int a = 0; a < MT; ++a)
; #pragma unroll
;       for (int nt = 0; nt < 4; ++nt)
;         ep(row0 + 16 * a, cbw + 16 * nt + 4 * q4, acc[a][nt][0], acc[a][nt][1], acc[a][nt][2], acc[a][nt][3]);
; DI void phase_resid(char* smem, const Params& p, int layer, const bf16_t* A, int K, const bf16_t* W, int gate_idx, bool first) {
;     ...
;   auto ep = [&](int row, int col, float v0, float v1, float v2, float v3) {
;     const int b = row / TT, t = row - b * TT;
;     const float4 g = *(const float4*)(p.mod + (size_t)(layer * 5 + (t < CTXL ? 4 : b)) * 6144 + gate_idx * 1024 + col);
;     const float4 xo = *(const float4*)(xsrc_row(p, first, row) + col);
;     *(float4*)(xdst_row(p, row) + col) = make_float4(xo.x + g.x * v0, xo.y + g.y * v1, xo.z + g.z * v2, xo.w + g.w * v3);
;   };
	v_pk_fma_f32 v[110:111], v[110:111], v[156:157], v[198:199]
	v_pk_fma_f32 v[112:113], v[112:113], v[158:159], v[200:201]
	v_pk_fma_f32 v[106:107], v[106:107], v[160:161], v[202:203]
	v_pk_fma_f32 v[108:109], v[108:109], v[162:163], v[204:205]
	v_pk_fma_f32 v[102:103], v[102:103], v[164:165], v[206:207]
	v_pk_fma_f32 v[104:105], v[104:105], v[166:167], v[208:209]
	v_pk_fma_f32 v[98:99], v[98:99], v[168:169], v[210:211]
	v_pk_fma_f32 v[100:101], v[100:101], v[170:171], v[212:213]
	global_store_dwordx4 v[140:141], v[110:113], off
	global_store_dwordx4 v[140:141], v[106:109], off offset:64
	global_store_dwordx4 v[140:141], v[102:105], off offset:128
	global_store_dwordx4 v[140:141], v[98:101], off offset:192
	v_add_co_u32_e32 v140, vcc, 0x10000, v140
	s_nop 1
	v_addc_co_u32_e32 v141, vcc, 0, v141, vcc
	global_load_dwordx4 v[198:201], v[138:139], off
	global_load_dwordx4 v[202:205], v[138:139], off offset:64
	global_load_dwordx4 v[206:209], v[138:139], off offset:128
	global_load_dwordx4 v[210:213], v[138:139], off offset:192
	v_add_co_u32_e32 v138, vcc, 0x10000, v138
	s_nop 1
	v_addc_co_u32_e32 v139, vcc, 0, v139, vcc
	s_waitcnt vmcnt(16)
	v_pk_fma_f32 v[94:95], v[94:95], v[156:157], v[214:215]
	v_pk_fma_f32 v[96:97], v[96:97], v[158:159], v[216:217]
	v_pk_fma_f32 v[90:91], v[90:91], v[160:161], v[218:219]
	v_pk_fma_f32 v[92:93], v[92:93], v[162:163], v[220:221]
	v_pk_fma_f32 v[86:87], v[86:87], v[164:165], v[222:223]
	v_pk_fma_f32 v[88:89], v[88:89], v[166:167], v[224:225]
	v_pk_fma_f32 v[82:83], v[82:83], v[168:169], v[142:143]
	v_pk_fma_f32 v[84:85], v[84:85], v[170:171], v[144:145]
	global_store_dwordx4 v[140:141], v[94:97], off
	global_store_dwordx4 v[140:141], v[90:93], off offset:64
	global_store_dwordx4 v[140:141], v[86:89], off offset:128
	global_store_dwordx4 v[140:141], v[82:85], off offset:192
	v_add_co_u32_e32 v140, vcc, 0x10000, v140
	s_nop 1
	v_addc_co_u32_e32 v141, vcc, 0, v141, vcc
	global_load_dwordx4 v[214:217], v[138:139], off
	global_load_dwordx4 v[218:221], v[138:139], off offset:64
	global_load_dwordx4 v[222:225], v[138:139], off offset:128
	global_load_dwordx4 v[142:145], v[138:139], off offset:192
	v_add_co_u32_e32 v138, vcc, 0x10000, v138
	s_nop 1
	v_addc_co_u32_e32 v139, vcc, 0, v139, vcc
	s_waitcnt vmcnt(16)
	v_pk_fma_f32 v[78:79], v[78:79], v[156:157], v[172:173]
	v_pk_fma_f32 v[80:81], v[80:81], v[158:159], v[174:175]
	v_pk_fma_f32 v[74:75], v[74:75], v[160:161], v[176:177]
	v_pk_fma_f32 v[76:77], v[76:77], v[162:163], v[178:179]
	v_pk_fma_f32 v[70:71], v[70:71], v[164:165], v[180:181]
	v_pk_fma_f32 v[72:73], v[72:73], v[166:167], v[182:183]
	v_pk_fma_f32 v[66:67], v[66:67], v[168:169], v[184:185]
	v_pk_fma_f32 v[68:69], v[68:69], v[170:171], v[186:187]
	global_store_dwordx4 v[140:141], v[78:81], off
	global_store_dwordx4 v[140:141], v[74:77], off offset:64
	global_store_dwordx4 v[140:141], v[70:73], off offset:128
	global_store_dwordx4 v[140:141], v[66:69], off offset:192
	v_add_co_u32_e32 v140, vcc, 0x10000, v140
	s_nop 1
	v_addc_co_u32_e32 v141, vcc, 0, v141, vcc
	global_load_dwordx4 v[172:175], v[138:139], off
	global_load_dwordx4 v[176:179], v[138:139], off offset:64
	global_load_dwordx4 v[180:183], v[138:139], off offset:128
	global_load_dwordx4 v[184:187], v[138:139], off offset:192
	v_add_co_u32_e32 v138, vcc, 0x10000, v138
	s_nop 1
	v_addc_co_u32_e32 v139, vcc, 0, v139, vcc
	s_waitcnt vmcnt(16)
	v_pk_fma_f32 v[62:63], v[62:63], v[156:157], v[198:199]
	v_pk_fma_f32 v[64:65], v[64:65], v[158:159], v[200:201]
	v_pk_fma_f32 v[58:59], v[58:59], v[160:161], v[202:203]
	v_pk_fma_f32 v[60:61], v[60:61], v[162:163], v[204:205]
	v_pk_fma_f32 v[54:55], v[54:55], v[164:165], v[206:207]
	v_pk_fma_f32 v[56:57], v[56:57], v[166:167], v[208:209]
	v_pk_fma_f32 v[50:51], v[50:51], v[168:169], v[210:211]
	v_pk_fma_f32 v[52:53], v[52:53], v[170:171], v[212:213]
	global_store_dwordx4 v[140:141], v[62:65], off
	global_store_dwordx4 v[140:141], v[58:61], off offset:64
	global_store_dwordx4 v[140:141], v[54:57], off offset:128
	global_store_dwordx4 v[140:141], v[50:53], off offset:192
	v_add_co_u32_e32 v140, vcc, 0x10000, v140
	s_nop 1
	v_addc_co_u32_e32 v141, vcc, 0, v141, vcc
	global_load_dwordx4 v[198:201], v[138:139], off
	global_load_dwordx4 v[202:205], v[138:139], off offset:64
	global_load_dwordx4 v[206:209], v[138:139], off offset:128
	global_load_dwordx4 v[210:213], v[138:139], off offset:192
	s_waitcnt vmcnt(16)
	v_pk_fma_f32 v[46:47], v[46:47], v[156:157], v[214:215]
	v_pk_fma_f32 v[48:49], v[48:49], v[158:159], v[216:217]
	v_pk_fma_f32 v[42:43], v[42:43], v[160:161], v[218:219]
	v_pk_fma_f32 v[44:45], v[44:45], v[162:163], v[220:221]
	v_pk_fma_f32 v[38:39], v[38:39], v[164:165], v[222:223]
	v_pk_fma_f32 v[40:41], v[40:41], v[166:167], v[224:225]
	v_pk_fma_f32 v[34:35], v[34:35], v[168:169], v[142:143]
	v_pk_fma_f32 v[36:37], v[36:37], v[170:171], v[144:145]
	global_store_dwordx4 v[140:141], v[46:49], off
	global_store_dwordx4 v[140:141], v[42:45], off offset:64
	global_store_dwordx4 v[140:141], v[38:41], off offset:128
	global_store_dwordx4 v[140:141], v[34:37], off offset:192
	v_add_co_u32_e32 v140, vcc, 0x10000, v140
	s_nop 1
	v_addc_co_u32_e32 v141, vcc, 0, v141, vcc
	s_waitcnt vmcnt(12)
	v_pk_fma_f32 v[30:31], v[30:31], v[156:157], v[172:173]
	v_pk_fma_f32 v[32:33], v[32:33], v[158:159], v[174:175]
	v_pk_fma_f32 v[26:27], v[26:27], v[160:161], v[176:177]
	v_pk_fma_f32 v[28:29], v[28:29], v[162:163], v[178:179]
	v_pk_fma_f32 v[22:23], v[22:23], v[164:165], v[180:181]
	v_pk_fma_f32 v[24:25], v[24:25], v[166:167], v[182:183]
	v_pk_fma_f32 v[18:19], v[18:19], v[168:169], v[184:185]
	v_pk_fma_f32 v[20:21], v[20:21], v[170:171], v[186:187]
	global_store_dwordx4 v[140:141], v[30:33], off
	global_store_dwordx4 v[140:141], v[26:29], off offset:64
	global_store_dwordx4 v[140:141], v[22:25], off offset:128
	global_store_dwordx4 v[140:141], v[18:21], off offset:192
	v_add_co_u32_e32 v140, vcc, 0x10000, v140
	s_nop 1
	v_addc_co_u32_e32 v141, vcc, 0, v141, vcc
	s_waitcnt vmcnt(8)
	v_pk_fma_f32 v[14:15], v[14:15], v[156:157], v[198:199]
	v_pk_fma_f32 v[16:17], v[16:17], v[158:159], v[200:201]
	v_pk_fma_f32 v[10:11], v[10:11], v[160:161], v[202:203]
	v_pk_fma_f32 v[12:13], v[12:13], v[162:163], v[204:205]
	v_pk_fma_f32 v[6:7], v[6:7], v[164:165], v[206:207]
	v_pk_fma_f32 v[8:9], v[8:9], v[166:167], v[208:209]
	v_pk_fma_f32 v[2:3], v[2:3], v[168:169], v[210:211]
	v_pk_fma_f32 v[4:5], v[4:5], v[170:171], v[212:213]
	global_store_dwordx4 v[140:141], v[14:17], off
	global_store_dwordx4 v[140:141], v[10:13], off offset:64
	global_store_dwordx4 v[140:141], v[6:9], off offset:128
	global_store_dwordx4 v[140:141], v[2:5], off offset:192
	s_branch .LBB0_41

; #define MFMA16(a, b, c) __builtin_amdgcn_mfma_f32_16x16x32_bf16((a), (b), (c), 0, 0, 0)
;     ...
;   for (int kt = 0; kt < nk; ++kt) {
;     const int buf = kt & 1;
;     const char* cA = smem + buf * STAGE + (wm * 32 * MI + r16) * 128;
;     const char* cB = smem + buf * STAGE + 32768 + (wn * 64 + r16) * 128;
; #pragma unroll
;     for (int k2 = 0; k2 < 2; ++k2) {
;       if (k2 == 1 && kt + 1 < nk) STAGE_TILE(buf ^ 1, (kt + 1) * 64)
;       const int po = ((4 * k2 + q4) ^ swz) * 16;
;       bf16x8 bf[4];
; #pragma unroll
;       for (int nt = 0; nt < 4; ++nt) bf[nt] = *(const bf16x8*)(cB + nt * 16 * 128 + po);
;       bf16x8 afc = *(const bf16x8*)(cA + po);
; #pragma unroll
;       for (int a = 0; a < MT; ++a) {
;         bf16x8 afn = afc;
;         if (a + 1 < MT) afn = *(const bf16x8*)(cA + (a + 1) * 16 * 128 + po);
;         __builtin_amdgcn_sched_barrier(0);
; #pragma unroll
;         for (int nt = 0; nt < 4; ++nt) acc[a][nt] = MFMA16(bf[nt], afc, acc[a][nt]);
;         __builtin_amdgcn_sched_barrier(0);
;         afc = afn;
;       }
;     }
;     asm volatile("s_waitcnt vmcnt(0)" ::: "memory");
;     __syncthreads();
;   }
.LBB0_75:
	s_and_b32 s41, s40, 0x10000
	s_add_i32 s42, s41, 0
	v_add_u32_e32 v190, s42, v147
	v_add_u32_e32 v162, v190, v146
	v_add_u32_e32 v149, s42, v148
	ds_read_b128 v[150:153], v162 offset:32768
	ds_read_b128 v[154:157], v162 offset:34816
	ds_read_b128 v[158:161], v162 offset:36864
	ds_read_b128 v[162:165], v162 offset:38912
	v_add_u32_e32 v202, v149, v146
	ds_read_b128 v[166:169], v202
	ds_read_b128 v[170:173], v202 offset:2048
	s_xor_b32 s41, s41, 0x10000
	s_waitcnt lgkmcnt(1)
	v_mfma_f32_16x16x32_bf16 v[126:129], v[150:153], v[166:169], v[126:129]
	v_readfirstlane_b32 s42, v145
	v_mfma_f32_16x16x32_bf16 v[122:125], v[154:157], v[166:169], v[122:125]
	s_nop 0
	v_mfma_f32_16x16x32_bf16 v[118:121], v[158:161], v[166:169], v[118:121]
	s_add_u32 s42, s42, s41
	v_mfma_f32_16x16x32_bf16 v[114:117], v[162:165], v[166:169], v[114:117]
	ds_read_b128 v[166:169], v202 offset:4096
	s_waitcnt lgkmcnt(1)
	v_mfma_f32_16x16x32_bf16 v[110:113], v[150:153], v[170:173], v[110:113]
	s_add_u32 m0, s42, 0x0
	v_mfma_f32_16x16x32_bf16 v[106:109], v[154:157], v[170:173], v[106:109]
	global_load_lds_dwordx4 v174, s[100:101]
	v_mfma_f32_16x16x32_bf16 v[102:105], v[158:161], v[170:173], v[102:105]
	s_add_u32 m0, s42, 0x2000
	v_mfma_f32_16x16x32_bf16 v[98:101], v[162:165], v[170:173], v[98:101]
	ds_read_b128 v[170:173], v202 offset:6144
	s_waitcnt lgkmcnt(1)
	v_mfma_f32_16x16x32_bf16 v[94:97], v[150:153], v[166:169], v[94:97]
	global_load_lds_dwordx4 v175, s[100:101]
	v_mfma_f32_16x16x32_bf16 v[90:93], v[154:157], v[166:169], v[90:93]
	s_add_u32 m0, s42, 0x4000
	v_mfma_f32_16x16x32_bf16 v[86:89], v[158:161], v[166:169], v[86:89]
	global_load_lds_dwordx4 v176, s[100:101]
	v_mfma_f32_16x16x32_bf16 v[82:85], v[162:165], v[166:169], v[82:85]
	ds_read_b128 v[166:169], v202 offset:8192
	s_waitcnt lgkmcnt(1)
	v_mfma_f32_16x16x32_bf16 v[78:81], v[150:153], v[170:173], v[78:81]
	s_add_u32 m0, s42, 0x6000
	v_mfma_f32_16x16x32_bf16 v[74:77], v[154:157], v[170:173], v[74:77]
	global_load_lds_dwordx4 v177, s[100:101]
	v_mfma_f32_16x16x32_bf16 v[70:73], v[158:161], v[170:173], v[70:73]
	s_add_u32 m0, s42, 0x8000
	v_mfma_f32_16x16x32_bf16 v[66:69], v[162:165], v[170:173], v[66:69]
	ds_read_b128 v[170:173], v202 offset:10240
	s_waitcnt lgkmcnt(1)
	v_mfma_f32_16x16x32_bf16 v[62:65], v[150:153], v[166:169], v[62:65]
	global_load_lds_dwordx4 v178, s[100:101]
	v_mfma_f32_16x16x32_bf16 v[58:61], v[154:157], v[166:169], v[58:61]
	s_add_u32 m0, s42, 0xa000
	v_mfma_f32_16x16x32_bf16 v[54:57], v[158:161], v[166:169], v[54:57]
	global_load_lds_dwordx4 v179, s[100:101]
	v_mfma_f32_16x16x32_bf16 v[50:53], v[162:165], v[166:169], v[50:53]
	ds_read_b128 v[166:169], v202 offset:12288
	s_waitcnt lgkmcnt(1)
	v_mfma_f32_16x16x32_bf16 v[46:49], v[150:153], v[170:173], v[46:49]
	s_add_u32 m0, s42, 0xc000
	v_mfma_f32_16x16x32_bf16 v[42:45], v[154:157], v[170:173], v[42:45]
	global_load_lds_dwordx4 v180, s[100:101]
	v_mfma_f32_16x16x32_bf16 v[38:41], v[158:161], v[170:173], v[38:41]
	s_add_u32 m0, s42, 0xe000
	v_mfma_f32_16x16x32_bf16 v[34:37], v[162:165], v[170:173], v[34:37]
	ds_read_b128 v[170:173], v202 offset:14336
	s_waitcnt lgkmcnt(1)
	v_mfma_f32_16x16x32_bf16 v[30:33], v[150:153], v[166:169], v[30:33]
	global_load_lds_dwordx4 v181, s[100:101]
	v_mfma_f32_16x16x32_bf16 v[26:29], v[154:157], v[166:169], v[26:29]
	v_mfma_f32_16x16x32_bf16 v[22:25], v[158:161], v[166:169], v[22:25]
	v_mfma_f32_16x16x32_bf16 v[18:21], v[162:165], v[166:169], v[18:21]
	s_waitcnt lgkmcnt(0)
	v_mfma_f32_16x16x32_bf16 v[14:17], v[150:153], v[170:173], v[14:17]
	v_mfma_f32_16x16x32_bf16 v[10:13], v[154:157], v[170:173], v[10:13]
	v_mfma_f32_16x16x32_bf16 v[6:9], v[158:161], v[170:173], v[6:9]
	v_mfma_f32_16x16x32_bf16 v[2:5], v[162:165], v[170:173], v[2:5]
	v_add_u32_e32 v162, v190, v144
	ds_read_b128 v[150:153], v162 offset:32768
	ds_read_b128 v[154:157], v162 offset:34816
	ds_read_b128 v[158:161], v162 offset:36864
	ds_read_b128 v[162:165], v162 offset:38912
	v_add_u32_e32 v149, v149, v144
	ds_read_b128 v[166:169], v149
	ds_read_b128 v[170:173], v149 offset:2048
	s_waitcnt lgkmcnt(0)
	v_mfma_f32_16x16x32_bf16 v[126:129], v[150:153], v[166:169], v[126:129]
	v_mfma_f32_16x16x32_bf16 v[122:125], v[154:157], v[166:169], v[122:125]
	v_mfma_f32_16x16x32_bf16 v[118:121], v[158:161], v[166:169], v[118:121]
	v_mfma_f32_16x16x32_bf16 v[114:117], v[162:165], v[166:169], v[114:117]
	ds_read_b128 v[166:169], v149 offset:4096
	v_mfma_f32_16x16x32_bf16 v[110:113], v[150:153], v[170:173], v[110:113]
	v_mfma_f32_16x16x32_bf16 v[106:109], v[154:157], v[170:173], v[106:109]
	v_mfma_f32_16x16x32_bf16 v[102:105], v[158:161], v[170:173], v[102:105]
	v_mfma_f32_16x16x32_bf16 v[98:101], v[162:165], v[170:173], v[98:101]
	ds_read_b128 v[170:173], v149 offset:6144
	s_waitcnt lgkmcnt(0)
	v_mfma_f32_16x16x32_bf16 v[94:97], v[150:153], v[166:169], v[94:97]
	v_mfma_f32_16x16x32_bf16 v[90:93], v[154:157], v[166:169], v[90:93]
	v_mfma_f32_16x16x32_bf16 v[86:89], v[158:161], v[166:169], v[86:89]
	v_mfma_f32_16x16x32_bf16 v[82:85], v[162:165], v[166:169], v[82:85]
	ds_read_b128 v[166:169], v149 offset:8192
	v_mfma_f32_16x16x32_bf16 v[78:81], v[150:153], v[170:173], v[78:81]
	v_mfma_f32_16x16x32_bf16 v[74:77], v[154:157], v[170:173], v[74:77]
	v_mfma_f32_16x16x32_bf16 v[70:73], v[158:161], v[170:173], v[70:73]
	v_mfma_f32_16x16x32_bf16 v[66:69], v[162:165], v[170:173], v[66:69]
	ds_read_b128 v[170:173], v149 offset:10240
	s_waitcnt lgkmcnt(0)
	v_mfma_f32_16x16x32_bf16 v[62:65], v[150:153], v[166:169], v[62:65]
	v_mfma_f32_16x16x32_bf16 v[58:61], v[154:157], v[166:169], v[58:61]
	v_mfma_f32_16x16x32_bf16 v[54:57], v[158:161], v[166:169], v[54:57]
	v_mfma_f32_16x16x32_bf16 v[50:53], v[162:165], v[166:169], v[50:53]
	ds_read_b128 v[166:169], v149 offset:12288
	v_mfma_f32_16x16x32_bf16 v[46:49], v[150:153], v[170:173], v[46:49]
	v_mfma_f32_16x16x32_bf16 v[42:45], v[154:157], v[170:173], v[42:45]
	v_mfma_f32_16x16x32_bf16 v[38:41], v[158:161], v[170:173], v[38:41]
	v_mfma_f32_16x16x32_bf16 v[34:37], v[162:165], v[170:173], v[34:37]
	ds_read_b128 v[170:173], v149 offset:14336
	s_waitcnt lgkmcnt(0)
	v_mfma_f32_16x16x32_bf16 v[30:33], v[150:153], v[166:169], v[30:33]
	v_mfma_f32_16x16x32_bf16 v[26:29], v[154:157], v[166:169], v[26:29]
	v_mfma_f32_16x16x32_bf16 v[22:25], v[158:161], v[166:169], v[22:25]
	v_mfma_f32_16x16x32_bf16 v[18:21], v[162:165], v[166:169], v[18:21]
	v_mfma_f32_16x16x32_bf16 v[14:17], v[150:153], v[170:173], v[14:17]
	v_mfma_f32_16x16x32_bf16 v[10:13], v[154:157], v[170:173], v[10:13]
	v_mfma_f32_16x16x32_bf16 v[6:9], v[158:161], v[170:173], v[6:9]
	v_mfma_f32_16x16x32_bf16 v[2:5], v[162:165], v[170:173], v[2:5]
	s_waitcnt vmcnt(0)
	s_add_u32 s100, s100, 0x80
	s_addc_u32 s101, s101, 0
	s_add_u32 s16, s16, 0x80
	s_addc_u32 s17, s17, 0
	s_add_i32 s40, s40, 0x10000
	s_cmpk_lg_i32 s16, 0x780
	s_waitcnt vmcnt(0)
	s_barrier
; #define MFMA16(a, b, c) __builtin_amdgcn_mfma_f32_16x16x32_bf16((a), (b), (c), 0, 0, 0)
;     ...
;   for (int kt = 0; kt < nk; ++kt) {
;     const int buf = kt & 1;
;     const char* cA = smem + buf * STAGE + (wm * 32 * MI + r16) * 128;
;     const char* cB = smem + buf * STAGE + 32768 + (wn * 64 + r16) * 128;
; #pragma unroll
;     for (int k2 = 0; k2 < 2; ++k2) {
;       if (k2 == 1 && kt + 1 < nk) STAGE_TILE(buf ^ 1, (kt + 1) * 64)
;       const int po = ((4 * k2 + q4) ^ swz) * 16;
;       bf16x8 bf[4];
; #pragma unroll
;       for (int nt = 0; nt < 4; ++nt) bf[nt] = *(const bf16x8*)(cB + nt * 16 * 128 + po);
;       bf16x8 afc = *(const bf16x8*)(cA + po);
; #pragma unroll
;       for (int a = 0; a < MT; ++a) {
;         bf16x8 afn = afc;
;         if (a + 1 < MT) afn = *(const bf16x8*)(cA + (a + 1) * 16 * 128 + po);
;         __builtin_amdgcn_sched_barrier(0);
; #pragma unroll
;         for (int nt = 0; nt < 4; ++nt) acc[a][nt] = MFMA16(bf[nt], afc, acc[a][nt]);
;         __builtin_amdgcn_sched_barrier(0);
;         afc = afn;
;       }
;     }
	s_cbranch_scc1 .LBB0_75
	s_add_i32 s16, 0, 0x10000
	v_add_u32_e32 v138, s16, v148
	v_readlane_b32 s16, v254, 18
	s_nop 1
	v_add_u32_e32 v139, s16, v147
	v_add_u32_e32 v145, v139, v146
	ds_read_b128 v[130:133], v145
	ds_read_b128 v[134:137], v145 offset:2048
	ds_read_b128 v[148:151], v145 offset:4096
	ds_read_b128 v[152:155], v145 offset:6144
	v_add_u32_e32 v145, v138, v146
	ds_read_b128 v[156:159], v145
	ds_read_b128 v[160:163], v145 offset:2048
	s_waitcnt lgkmcnt(1)
	v_mfma_f32_16x16x32_bf16 v[126:129], v[130:133], v[156:159], v[126:129]
	v_mfma_f32_16x16x32_bf16 v[122:125], v[134:137], v[156:159], v[122:125]
	v_mfma_f32_16x16x32_bf16 v[118:121], v[148:151], v[156:159], v[118:121]
	v_mfma_f32_16x16x32_bf16 v[114:117], v[152:155], v[156:159], v[114:117]
	ds_read_b128 v[156:159], v145 offset:4096
	s_waitcnt lgkmcnt(1)
	v_mfma_f32_16x16x32_bf16 v[110:113], v[130:133], v[160:163], v[110:113]
	v_mfma_f32_16x16x32_bf16 v[106:109], v[134:137], v[160:163], v[106:109]
	v_mfma_f32_16x16x32_bf16 v[102:105], v[148:151], v[160:163], v[102:105]
	v_mfma_f32_16x16x32_bf16 v[98:101], v[152:155], v[160:163], v[98:101]
	ds_read_b128 v[160:163], v145 offset:6144
	s_waitcnt lgkmcnt(1)
	v_mfma_f32_16x16x32_bf16 v[94:97], v[130:133], v[156:159], v[94:97]
	v_mfma_f32_16x16x32_bf16 v[90:93], v[134:137], v[156:159], v[90:93]
	v_mfma_f32_16x16x32_bf16 v[86:89], v[148:151], v[156:159], v[86:89]
	v_mfma_f32_16x16x32_bf16 v[82:85], v[152:155], v[156:159], v[82:85]
	ds_read_b128 v[156:159], v145 offset:8192
	s_waitcnt lgkmcnt(1)
	v_mfma_f32_16x16x32_bf16 v[78:81], v[130:133], v[160:163], v[78:81]
	v_mfma_f32_16x16x32_bf16 v[74:77], v[134:137], v[160:163], v[74:77]
	v_mfma_f32_16x16x32_bf16 v[70:73], v[148:151], v[160:163], v[70:73]
	v_mfma_f32_16x16x32_bf16 v[66:69], v[152:155], v[160:163], v[66:69]
	ds_read_b128 v[160:163], v145 offset:10240
	s_waitcnt lgkmcnt(1)
	v_mfma_f32_16x16x32_bf16 v[62:65], v[130:133], v[156:159], v[62:65]
	v_mfma_f32_16x16x32_bf16 v[58:61], v[134:137], v[156:159], v[58:61]
	v_mfma_f32_16x16x32_bf16 v[54:57], v[148:151], v[156:159], v[54:57]
	v_mfma_f32_16x16x32_bf16 v[50:53], v[152:155], v[156:159], v[50:53]
	ds_read_b128 v[156:159], v145 offset:12288
	s_waitcnt lgkmcnt(1)
	v_mfma_f32_16x16x32_bf16 v[46:49], v[130:133], v[160:163], v[46:49]
	v_mfma_f32_16x16x32_bf16 v[42:45], v[134:137], v[160:163], v[42:45]
	v_mfma_f32_16x16x32_bf16 v[38:41], v[148:151], v[160:163], v[38:41]
	v_mfma_f32_16x16x32_bf16 v[34:37], v[152:155], v[160:163], v[34:37]
	ds_read_b128 v[160:163], v145 offset:14336
	s_waitcnt lgkmcnt(1)
	v_mfma_f32_16x16x32_bf16 v[30:33], v[130:133], v[156:159], v[30:33]
	v_mfma_f32_16x16x32_bf16 v[26:29], v[134:137], v[156:159], v[26:29]
	v_mfma_f32_16x16x32_bf16 v[22:25], v[148:151], v[156:159], v[22:25]
	v_mfma_f32_16x16x32_bf16 v[18:21], v[152:155], v[156:159], v[18:21]
	s_waitcnt lgkmcnt(0)
	v_mfma_f32_16x16x32_bf16 v[14:17], v[130:133], v[160:163], v[14:17]
	v_mfma_f32_16x16x32_bf16 v[10:13], v[134:137], v[160:163], v[10:13]
	v_mfma_f32_16x16x32_bf16 v[6:9], v[148:151], v[160:163], v[6:9]
	v_mfma_f32_16x16x32_bf16 v[2:5], v[152:155], v[160:163], v[2:5]
	v_add_u32_e32 v139, v139, v144
	ds_read_b128 v[130:133], v139
	ds_read_b128 v[134:137], v139 offset:2048
	ds_read_b128 v[146:149], v139 offset:4096
	ds_read_b128 v[150:153], v139 offset:6144
	v_add_u32_e32 v138, v138, v144
	ds_read_b128 v[154:157], v138
	ds_read_b128 v[158:161], v138 offset:2048
	s_waitcnt lgkmcnt(1)
	v_mfma_f32_16x16x32_bf16 v[126:129], v[130:133], v[154:157], v[126:129]
	v_mfma_f32_16x16x32_bf16 v[122:125], v[134:137], v[154:157], v[122:125]
	v_mfma_f32_16x16x32_bf16 v[118:121], v[146:149], v[154:157], v[118:121]
	v_mfma_f32_16x16x32_bf16 v[114:117], v[150:153], v[154:157], v[114:117]
	ds_read_b128 v[154:157], v138 offset:4096
	s_waitcnt lgkmcnt(1)
	v_mfma_f32_16x16x32_bf16 v[162:165], v[130:133], v[158:161], v[110:113]
	v_mfma_f32_16x16x32_bf16 v[166:169], v[134:137], v[158:161], v[106:109]
	v_mfma_f32_16x16x32_bf16 v[102:105], v[146:149], v[158:161], v[102:105]
	v_mfma_f32_16x16x32_bf16 v[98:101], v[150:153], v[158:161], v[98:101]
	s_nop 0
	ds_read_b128 v[106:109], v138 offset:6144
	s_waitcnt lgkmcnt(1)
	v_mfma_f32_16x16x32_bf16 v[94:97], v[130:133], v[154:157], v[94:97]
	v_mfma_f32_16x16x32_bf16 v[90:93], v[134:137], v[154:157], v[90:93]
	v_mfma_f32_16x16x32_bf16 v[86:89], v[146:149], v[154:157], v[86:89]
	v_mfma_f32_16x16x32_bf16 v[82:85], v[150:153], v[154:157], v[82:85]
	ds_read_b128 v[110:113], v138 offset:8192
	s_waitcnt lgkmcnt(1)
	v_mfma_f32_16x16x32_bf16 v[78:81], v[130:133], v[106:109], v[78:81]
	v_mfma_f32_16x16x32_bf16 v[74:77], v[134:137], v[106:109], v[74:77]
	v_mfma_f32_16x16x32_bf16 v[70:73], v[146:149], v[106:109], v[70:73]
	v_mfma_f32_16x16x32_bf16 v[66:69], v[150:153], v[106:109], v[66:69]
	ds_read_b128 v[106:109], v138 offset:10240
	s_waitcnt lgkmcnt(1)
	v_mfma_f32_16x16x32_bf16 v[62:65], v[130:133], v[110:113], v[62:65]
	v_mfma_f32_16x16x32_bf16 v[58:61], v[134:137], v[110:113], v[58:61]
	v_mfma_f32_16x16x32_bf16 v[54:57], v[146:149], v[110:113], v[54:57]
	v_mfma_f32_16x16x32_bf16 v[50:53], v[150:153], v[110:113], v[50:53]
	ds_read_b128 v[110:113], v138 offset:12288
	s_waitcnt lgkmcnt(1)
	v_mfma_f32_16x16x32_bf16 v[46:49], v[130:133], v[106:109], v[46:49]
	v_mfma_f32_16x16x32_bf16 v[42:45], v[134:137], v[106:109], v[42:45]
	v_mfma_f32_16x16x32_bf16 v[38:41], v[146:149], v[106:109], v[38:41]
	v_mfma_f32_16x16x32_bf16 v[34:37], v[150:153], v[106:109], v[34:37]
	ds_read_b128 v[106:109], v138 offset:14336
	s_waitcnt lgkmcnt(1)
; DI unsigned pack2(float a, float b) { hwf2_t f = {a, b}; return __builtin_bit_cast(unsigned, __builtin_convertvector(f, hwbf2_t)); }
; DI float fsigmoid(float x) { return __builtin_amdgcn_rcpf(1.f + __expf(-x)); }
; DI void phase_ffn_up(char* smem, const Params& p, int layer) {
;     ...
;   auto ep = [=](int row, int cb, int q4, const f32x4& c0, const f32x4& c1, const f32x4& c2, const f32x4& c3) {
;     const uint4 o = make_uint4(pack2(c0[0] * fsigmoid(c0[0]) * c0[1], c0[2] * fsigmoid(c0[2]) * c0[3]),
;                                pack2(c1[0] * fsigmoid(c1[0]) * c1[1], c1[2] * fsigmoid(c1[2]) * c1[3]),
;                                pack2(c2[0] * fsigmoid(c2[0]) * c2[1], c2[2] * fsigmoid(c2[2]) * c2[3]),
;                                pack2(c3[0] * fsigmoid(c3[0]) * c3[1], c3[2] * fsigmoid(c3[2]) * c3[3]));
;     *(uint4*)(Hh + (size_t)row * FH + (cb >> 1) + q4 * 8) = o;
;   };
	v_mfma_f32_16x16x32_bf16 v[30:33], v[130:133], v[110:113], v[30:33]
	v_mfma_f32_16x16x32_bf16 v[26:29], v[134:137], v[110:113], v[26:29]
	v_mfma_f32_16x16x32_bf16 v[22:25], v[146:149], v[110:113], v[22:25]
	v_mfma_f32_16x16x32_bf16 v[18:21], v[150:153], v[110:113], v[18:21]
	s_waitcnt lgkmcnt(0)
	v_mfma_f32_16x16x32_bf16 v[14:17], v[130:133], v[106:109], v[14:17]
	v_mfma_f32_16x16x32_bf16 v[10:13], v[134:137], v[106:109], v[10:13]
	v_mfma_f32_16x16x32_bf16 v[6:9], v[146:149], v[106:109], v[6:9]
	v_mfma_f32_16x16x32_bf16 v[2:5], v[150:153], v[106:109], v[2:5]
	v_or_b32_e32 v107, s38, v142
	v_lshl_add_u32 v110, v141, 7, v107
	v_mul_f32_e32 v107, 0xbfb8aa3b, v126
	v_mul_f32_e32 v108, 0xbfb8aa3b, v128
	v_exp_f32_e32 v107, v107
	v_exp_f32_e32 v109, v108
	v_lshl_or_b32 v106, v143, 6, s39
	v_ashrrev_i32_e32 v108, 1, v106
	v_add_f32_e32 v106, 1.0, v107
	v_add_f32_e32 v107, 1.0, v109
	v_rcp_f32_e32 v106, v106
	v_rcp_f32_e32 v107, v107
	v_mov_b32_e32 v112, v126
	v_mov_b32_e32 v113, v128
	v_mul_f32_e32 v111, 0xbfb8aa3b, v122
	v_pk_mul_f32 v[106:107], v[112:113], v[106:107]
	v_exp_f32_e32 v111, v111
	v_mul_f32_e32 v112, 0xbfb8aa3b, v124
	v_exp_f32_e32 v113, v112
	v_mov_b32_e32 v128, v127
	v_add_f32_e32 v111, 1.0, v111
	v_rcp_f32_e32 v112, v111
	v_add_f32_e32 v111, 1.0, v113
	v_rcp_f32_e32 v113, v111
	v_pk_mul_f32 v[106:107], v[128:129], v[106:107]
	v_mul_f32_e32 v111, 0xbfb8aa3b, v118
	v_cvt_pk_bf16_f32 v126, v106, v107
	v_mov_b32_e32 v106, v122
	v_mov_b32_e32 v107, v124
	v_pk_mul_f32 v[106:107], v[106:107], v[112:113]
	v_exp_f32_e32 v111, v111
	v_mul_f32_e32 v112, 0xbfb8aa3b, v120
	v_exp_f32_e32 v113, v112
	v_mov_b32_e32 v124, v123
	v_add_f32_e32 v111, 1.0, v111
	v_rcp_f32_e32 v112, v111
	v_add_f32_e32 v111, 1.0, v113
	v_rcp_f32_e32 v113, v111
	v_pk_mul_f32 v[106:107], v[124:125], v[106:107]
	v_mul_f32_e32 v111, 0xbfb8aa3b, v114
	v_cvt_pk_bf16_f32 v127, v106, v107
	v_mov_b32_e32 v106, v118
	v_mov_b32_e32 v107, v120
	v_pk_mul_f32 v[106:107], v[106:107], v[112:113]
	v_exp_f32_e32 v111, v111
	v_mul_f32_e32 v112, 0xbfb8aa3b, v116
	v_exp_f32_e32 v113, v112
	v_mov_b32_e32 v120, v119
	v_add_f32_e32 v111, 1.0, v111
	v_rcp_f32_e32 v112, v111
	v_add_f32_e32 v111, 1.0, v113
	v_rcp_f32_e32 v113, v111
	v_pk_mul_f32 v[106:107], v[120:121], v[106:107]
	v_readlane_b32 s52, v253, 40
	v_cvt_pk_bf16_f32 v128, v106, v107
	v_mov_b32_e32 v106, v114
	v_mov_b32_e32 v107, v116
	v_pk_mul_f32 v[106:107], v[106:107], v[112:113]
	v_mov_b32_e32 v116, v115
	v_mul_f32_e32 v111, 0xbfb8aa3b, v162
	v_pk_mul_f32 v[106:107], v[116:117], v[106:107]
	v_readlane_b32 s54, v253, 42
	v_readlane_b32 s55, v253, 43
	v_exp_f32_e32 v111, v111
	v_mul_f32_e32 v114, 0xbfb8aa3b, v164
	v_ashrrev_i32_e32 v109, 31, v108
	v_cvt_pk_bf16_f32 v129, v106, v107
	v_mov_b64_e32 v[106:107], s[54:55]
	s_movk_i32 s38, 0x1600
	v_exp_f32_e32 v114, v114
	v_mad_i64_i32 v[112:113], s[16:17], v110, s38, v[106:107]
	v_lshlrev_b64 v[108:109], 1, v[108:109]
	v_lshl_add_u64 v[112:113], v[112:113], 0, v[108:109]
	v_lshlrev_b32_e32 v190, 4, v140
	v_lshl_add_u64 v[112:113], v[112:113], 0, v[190:191]
	v_add_f32_e32 v111, 1.0, v111
	s_waitcnt vmcnt(0)
	s_barrier
	global_store_dwordx4 v[112:113], v[126:129], off
	v_rcp_f32_e32 v112, v111
	v_add_f32_e32 v111, 1.0, v114
	v_rcp_f32_e32 v113, v111
	v_mov_b32_e32 v114, v162
	v_mov_b32_e32 v115, v164
	v_mov_b32_e32 v164, v163
	v_pk_mul_f32 v[112:113], v[114:115], v[112:113]
	v_mul_f32_e32 v114, 0xbfb8aa3b, v166
	v_mul_f32_e32 v115, 0xbfb8aa3b, v168
	v_exp_f32_e32 v114, v114
	v_exp_f32_e32 v115, v115
	v_pk_mul_f32 v[112:113], v[164:165], v[112:113]
	v_mov_b32_e32 v116, v166
	v_add_f32_e32 v114, 1.0, v114
	v_add_f32_e32 v115, 1.0, v115
	v_rcp_f32_e32 v114, v114
	v_rcp_f32_e32 v115, v115
	v_cvt_pk_bf16_f32 v112, v112, v113
	v_mov_b32_e32 v117, v168
	v_mul_f32_e32 v113, 0xbfb8aa3b, v102
	v_pk_mul_f32 v[114:115], v[116:117], v[114:115]
	v_exp_f32_e32 v113, v113
	v_mul_f32_e32 v116, 0xbfb8aa3b, v104
	v_exp_f32_e32 v117, v116
	v_mov_b32_e32 v168, v167
	v_add_f32_e32 v113, 1.0, v113
	v_rcp_f32_e32 v116, v113
	v_add_f32_e32 v113, 1.0, v117
	v_rcp_f32_e32 v117, v113
	v_pk_mul_f32 v[114:115], v[168:169], v[114:115]
	v_or_b32_e32 v111, 16, v110
	v_cvt_pk_bf16_f32 v113, v114, v115
	v_mov_b32_e32 v114, v102
	v_mov_b32_e32 v115, v104
	v_mul_f32_e32 v102, 0xbfb8aa3b, v98
	v_pk_mul_f32 v[114:115], v[114:115], v[116:117]
	v_exp_f32_e32 v116, v102
	v_mul_f32_e32 v102, 0xbfb8aa3b, v100
	v_exp_f32_e32 v117, v102
	v_mov_b32_e32 v104, v103
	v_pk_mul_f32 v[102:103], v[104:105], v[114:115]
	v_add_f32_e32 v104, 1.0, v116
	v_add_f32_e32 v105, 1.0, v117
	v_rcp_f32_e32 v104, v104
	v_rcp_f32_e32 v105, v105
	v_cvt_pk_bf16_f32 v114, v102, v103
	v_mov_b32_e32 v102, v98
	v_mov_b32_e32 v103, v100
	v_pk_mul_f32 v[102:103], v[102:103], v[104:105]
	v_mov_b32_e32 v100, v99
	v_pk_mul_f32 v[98:99], v[100:101], v[102:103]
	v_mul_f32_e32 v100, 0xbfb8aa3b, v94
	v_mul_f32_e32 v101, 0xbfb8aa3b, v96
	v_exp_f32_e32 v100, v100
	v_exp_f32_e32 v101, v101
	v_cvt_pk_bf16_f32 v115, v98, v99
	v_mad_i64_i32 v[98:99], s[16:17], v111, s38, v[106:107]
	v_lshl_add_u64 v[98:99], v[98:99], 0, v[108:109]
	v_lshl_add_u64 v[98:99], v[98:99], 0, v[190:191]
	global_store_dwordx4 v[98:99], v[112:115], off
	v_add_f32_e32 v98, 1.0, v100
	v_add_f32_e32 v99, 1.0, v101
	v_rcp_f32_e32 v98, v98
	v_rcp_f32_e32 v99, v99
	v_mov_b32_e32 v100, v94
	v_mov_b32_e32 v101, v96
	v_mul_f32_e32 v94, 0xbfb8aa3b, v90
	v_pk_mul_f32 v[98:99], v[100:101], v[98:99]
	v_exp_f32_e32 v100, v94
	v_mul_f32_e32 v94, 0xbfb8aa3b, v92
	v_exp_f32_e32 v101, v94
	v_mov_b32_e32 v96, v95
	v_pk_mul_f32 v[94:95], v[96:97], v[98:99]
	v_add_f32_e32 v96, 1.0, v100
	v_add_f32_e32 v97, 1.0, v101
; DI unsigned pack2(float a, float b) { hwf2_t f = {a, b}; return __builtin_bit_cast(unsigned, __builtin_convertvector(f, hwbf2_t)); }
; DI float fsigmoid(float x) { return __builtin_amdgcn_rcpf(1.f + __expf(-x)); }
; DI void phase_ffn_up(char* smem, const Params& p, int layer) {
;     ...
;   auto ep = [=](int row, int cb, int q4, const f32x4& c0, const f32x4& c1, const f32x4& c2, const f32x4& c3) {
;     const uint4 o = make_uint4(pack2(c0[0] * fsigmoid(c0[0]) * c0[1], c0[2] * fsigmoid(c0[2]) * c0[3]),
;                                pack2(c1[0] * fsigmoid(c1[0]) * c1[1], c1[2] * fsigmoid(c1[2]) * c1[3]),
;                                pack2(c2[0] * fsigmoid(c2[0]) * c2[1], c2[2] * fsigmoid(c2[2]) * c2[3]),
;                                pack2(c3[0] * fsigmoid(c3[0]) * c3[1], c3[2] * fsigmoid(c3[2]) * c3[3]));
;     *(uint4*)(Hh + (size_t)row * FH + (cb >> 1) + q4 * 8) = o;
;   };
	v_rcp_f32_e32 v96, v96
	v_rcp_f32_e32 v97, v97
	v_mov_b32_e32 v98, v90
	v_mul_f32_e32 v90, 0xbfb8aa3b, v86
	v_cvt_pk_bf16_f32 v94, v94, v95
	v_mov_b32_e32 v99, v92
	v_exp_f32_e32 v95, v90
	v_mul_f32_e32 v90, 0xbfb8aa3b, v88
	v_pk_mul_f32 v[96:97], v[98:99], v[96:97]
	v_exp_f32_e32 v98, v90
	v_mov_b32_e32 v92, v91
	v_pk_mul_f32 v[90:91], v[92:93], v[96:97]
	v_add_f32_e32 v92, 1.0, v95
	v_add_f32_e32 v93, 1.0, v98
	v_rcp_f32_e32 v92, v92
	v_rcp_f32_e32 v93, v93
	v_cvt_pk_bf16_f32 v95, v90, v91
	v_mov_b32_e32 v90, v86
	v_mov_b32_e32 v91, v88
	v_mul_f32_e32 v86, 0xbfb8aa3b, v82
	v_pk_mul_f32 v[90:91], v[90:91], v[92:93]
	v_exp_f32_e32 v92, v86
	v_mul_f32_e32 v86, 0xbfb8aa3b, v84
	v_exp_f32_e32 v93, v86
	v_mov_b32_e32 v88, v87
	v_pk_mul_f32 v[86:87], v[88:89], v[90:91]
	v_add_f32_e32 v88, 1.0, v92
	v_add_f32_e32 v89, 1.0, v93
	v_rcp_f32_e32 v88, v88
	v_rcp_f32_e32 v89, v89
	v_cvt_pk_bf16_f32 v96, v86, v87
	v_mov_b32_e32 v86, v82
	v_mov_b32_e32 v87, v84
	v_pk_mul_f32 v[86:87], v[86:87], v[88:89]
	v_mov_b32_e32 v84, v83
	v_pk_mul_f32 v[82:83], v[84:85], v[86:87]
	v_mul_f32_e32 v84, 0xbfb8aa3b, v78
	v_mul_f32_e32 v85, 0xbfb8aa3b, v80
	v_or_b32_e32 v102, 32, v110
	v_exp_f32_e32 v84, v84
	v_exp_f32_e32 v85, v85
	v_cvt_pk_bf16_f32 v97, v82, v83
	v_mad_i64_i32 v[82:83], s[16:17], v102, s38, v[106:107]
	v_lshl_add_u64 v[82:83], v[82:83], 0, v[108:109]
	v_lshl_add_u64 v[82:83], v[82:83], 0, v[190:191]
	global_store_dwordx4 v[82:83], v[94:97], off
	v_add_f32_e32 v82, 1.0, v84
	v_add_f32_e32 v83, 1.0, v85
	v_rcp_f32_e32 v82, v82
	v_rcp_f32_e32 v83, v83
	v_mov_b32_e32 v84, v78
	v_mov_b32_e32 v85, v80
	v_mul_f32_e32 v78, 0xbfb8aa3b, v74
	v_pk_mul_f32 v[82:83], v[84:85], v[82:83]
	v_exp_f32_e32 v84, v78
	v_mul_f32_e32 v78, 0xbfb8aa3b, v76
	v_exp_f32_e32 v85, v78
	v_mov_b32_e32 v80, v79
	v_pk_mul_f32 v[78:79], v[80:81], v[82:83]
	v_add_f32_e32 v80, 1.0, v84
	v_add_f32_e32 v81, 1.0, v85
	v_rcp_f32_e32 v80, v80
	v_rcp_f32_e32 v81, v81
	v_mov_b32_e32 v82, v74
	v_mul_f32_e32 v74, 0xbfb8aa3b, v70
	v_cvt_pk_bf16_f32 v78, v78, v79
	v_mov_b32_e32 v83, v76
	v_exp_f32_e32 v79, v74
	v_mul_f32_e32 v74, 0xbfb8aa3b, v72
	v_pk_mul_f32 v[80:81], v[82:83], v[80:81]
	v_exp_f32_e32 v82, v74
	v_mov_b32_e32 v76, v75
	v_pk_mul_f32 v[74:75], v[76:77], v[80:81]
	v_add_f32_e32 v76, 1.0, v79
	v_add_f32_e32 v77, 1.0, v82
	v_rcp_f32_e32 v76, v76
	v_rcp_f32_e32 v77, v77
	v_cvt_pk_bf16_f32 v79, v74, v75
	v_mov_b32_e32 v74, v70
	v_mov_b32_e32 v75, v72
	v_mul_f32_e32 v70, 0xbfb8aa3b, v66
	v_pk_mul_f32 v[74:75], v[74:75], v[76:77]
	v_exp_f32_e32 v76, v70
	v_mul_f32_e32 v70, 0xbfb8aa3b, v68
	v_exp_f32_e32 v77, v70
	v_mov_b32_e32 v72, v71
	v_pk_mul_f32 v[70:71], v[72:73], v[74:75]
	v_add_f32_e32 v72, 1.0, v76
	v_add_f32_e32 v73, 1.0, v77
	v_rcp_f32_e32 v72, v72
	v_rcp_f32_e32 v73, v73
	v_cvt_pk_bf16_f32 v80, v70, v71
	v_mov_b32_e32 v70, v66
	v_mov_b32_e32 v71, v68
	v_pk_mul_f32 v[70:71], v[70:71], v[72:73]
	v_mov_b32_e32 v68, v67
	v_pk_mul_f32 v[66:67], v[68:69], v[70:71]
	v_mul_f32_e32 v68, 0xbfb8aa3b, v62
	v_mul_f32_e32 v69, 0xbfb8aa3b, v64
	v_or_b32_e32 v86, 48, v110
	v_exp_f32_e32 v68, v68
	v_exp_f32_e32 v69, v69
	v_cvt_pk_bf16_f32 v81, v66, v67
	v_mad_i64_i32 v[66:67], s[16:17], v86, s38, v[106:107]
	v_lshl_add_u64 v[66:67], v[66:67], 0, v[108:109]
	v_lshl_add_u64 v[66:67], v[66:67], 0, v[190:191]
	global_store_dwordx4 v[66:67], v[78:81], off
	v_add_f32_e32 v66, 1.0, v68
	v_add_f32_e32 v67, 1.0, v69
	v_rcp_f32_e32 v66, v66
	v_rcp_f32_e32 v67, v67
	v_mov_b32_e32 v68, v62
	v_mov_b32_e32 v69, v64
	v_mul_f32_e32 v62, 0xbfb8aa3b, v58
	v_pk_mul_f32 v[66:67], v[68:69], v[66:67]
	v_exp_f32_e32 v68, v62
	v_mul_f32_e32 v62, 0xbfb8aa3b, v60
	v_exp_f32_e32 v69, v62
	v_mov_b32_e32 v64, v63
	v_pk_mul_f32 v[62:63], v[64:65], v[66:67]
	v_add_f32_e32 v64, 1.0, v68
	v_add_f32_e32 v65, 1.0, v69
	v_rcp_f32_e32 v64, v64
	v_rcp_f32_e32 v65, v65
	v_mov_b32_e32 v66, v58
	v_mul_f32_e32 v58, 0xbfb8aa3b, v54
	v_cvt_pk_bf16_f32 v62, v62, v63
	v_mov_b32_e32 v67, v60
	v_exp_f32_e32 v63, v58
	v_mul_f32_e32 v58, 0xbfb8aa3b, v56
	v_pk_mul_f32 v[64:65], v[66:67], v[64:65]
	v_exp_f32_e32 v66, v58
	v_mov_b32_e32 v60, v59
	v_pk_mul_f32 v[58:59], v[60:61], v[64:65]
	v_add_f32_e32 v60, 1.0, v63
	v_add_f32_e32 v61, 1.0, v66
	v_rcp_f32_e32 v60, v60
	v_rcp_f32_e32 v61, v61
	v_cvt_pk_bf16_f32 v63, v58, v59
	v_mov_b32_e32 v58, v54
	v_mov_b32_e32 v59, v56
	v_mul_f32_e32 v54, 0xbfb8aa3b, v50
	v_pk_mul_f32 v[58:59], v[58:59], v[60:61]
	v_exp_f32_e32 v60, v54
	v_mul_f32_e32 v54, 0xbfb8aa3b, v52
	v_exp_f32_e32 v61, v54
	v_mov_b32_e32 v56, v55
	v_pk_mul_f32 v[54:55], v[56:57], v[58:59]
	v_add_f32_e32 v56, 1.0, v60
	v_add_f32_e32 v57, 1.0, v61
	v_rcp_f32_e32 v56, v56
	v_rcp_f32_e32 v57, v57
	v_cvt_pk_bf16_f32 v64, v54, v55
	v_mov_b32_e32 v54, v50
	v_mov_b32_e32 v55, v52
	v_pk_mul_f32 v[54:55], v[54:55], v[56:57]
	v_mov_b32_e32 v52, v51
	v_pk_mul_f32 v[50:51], v[52:53], v[54:55]
	v_mul_f32_e32 v52, 0xbfb8aa3b, v46
	v_mul_f32_e32 v53, 0xbfb8aa3b, v48
	v_or_b32_e32 v70, 64, v110
	v_exp_f32_e32 v52, v52
	v_exp_f32_e32 v53, v53
	v_cvt_pk_bf16_f32 v65, v50, v51
	v_mad_i64_i32 v[50:51], s[16:17], v70, s38, v[106:107]
	v_lshl_add_u64 v[50:51], v[50:51], 0, v[108:109]
	v_lshl_add_u64 v[50:51], v[50:51], 0, v[190:191]
	global_store_dwordx4 v[50:51], v[62:65], off
	v_add_f32_e32 v50, 1.0, v52
	v_add_f32_e32 v51, 1.0, v53
	v_rcp_f32_e32 v50, v50
	v_rcp_f32_e32 v51, v51
	v_mov_b32_e32 v52, v46
	v_mov_b32_e32 v53, v48
	v_mul_f32_e32 v46, 0xbfb8aa3b, v42
	v_pk_mul_f32 v[50:51], v[52:53], v[50:51]
	v_exp_f32_e32 v52, v46
	v_mul_f32_e32 v46, 0xbfb8aa3b, v44
	v_exp_f32_e32 v53, v46
	v_mov_b32_e32 v48, v47
	v_pk_mul_f32 v[46:47], v[48:49], v[50:51]
; DI unsigned pack2(float a, float b) { hwf2_t f = {a, b}; return __builtin_bit_cast(unsigned, __builtin_convertvector(f, hwbf2_t)); }
; DI float fsigmoid(float x) { return __builtin_amdgcn_rcpf(1.f + __expf(-x)); }
; template <int TMI, class F>
; DI void for_tiles_xcd(int MT, int NT, const F& f) {
;     ...
;     for (int c = x; c * 32 < total_full; c += 8)
;       for (int kk = slot; kk < 32; kk += nslots) {
;         const int L = c * 32 + kk;
;         if (L >= total_full) break;
;         int mt, nt; decode(L, mt, nt);
;         f(mt * 256, nt, std::integral_constant<int, 4>{});
; DI void phase_ffn_up(char* smem, const Params& p, int layer) {
;     ...
;   auto ep = [=](int row, int cb, int q4, const f32x4& c0, const f32x4& c1, const f32x4& c2, const f32x4& c3) {
;     const uint4 o = make_uint4(pack2(c0[0] * fsigmoid(c0[0]) * c0[1], c0[2] * fsigmoid(c0[2]) * c0[3]),
;                                pack2(c1[0] * fsigmoid(c1[0]) * c1[1], c1[2] * fsigmoid(c1[2]) * c1[3]),
;                                pack2(c2[0] * fsigmoid(c2[0]) * c2[1], c2[2] * fsigmoid(c2[2]) * c2[3]),
;                                pack2(c3[0] * fsigmoid(c3[0]) * c3[1], c3[2] * fsigmoid(c3[2]) * c3[3]));
;     *(uint4*)(Hh + (size_t)row * FH + (cb >> 1) + q4 * 8) = o;
;   };
	v_add_f32_e32 v48, 1.0, v52
	v_add_f32_e32 v49, 1.0, v53
	v_rcp_f32_e32 v48, v48
	v_rcp_f32_e32 v49, v49
	v_mov_b32_e32 v50, v42
	v_mul_f32_e32 v42, 0xbfb8aa3b, v38
	v_cvt_pk_bf16_f32 v46, v46, v47
	v_mov_b32_e32 v51, v44
	v_exp_f32_e32 v47, v42
	v_mul_f32_e32 v42, 0xbfb8aa3b, v40
	v_pk_mul_f32 v[48:49], v[50:51], v[48:49]
	v_exp_f32_e32 v50, v42
	v_mov_b32_e32 v44, v43
	v_pk_mul_f32 v[42:43], v[44:45], v[48:49]
	v_add_f32_e32 v44, 1.0, v47
	v_add_f32_e32 v45, 1.0, v50
	v_rcp_f32_e32 v44, v44
	v_rcp_f32_e32 v45, v45
	v_cvt_pk_bf16_f32 v47, v42, v43
	v_mov_b32_e32 v42, v38
	v_mov_b32_e32 v43, v40
	v_mul_f32_e32 v38, 0xbfb8aa3b, v34
	v_pk_mul_f32 v[42:43], v[42:43], v[44:45]
	v_exp_f32_e32 v44, v38
	v_mul_f32_e32 v38, 0xbfb8aa3b, v36
	v_exp_f32_e32 v45, v38
	v_mov_b32_e32 v40, v39
	v_pk_mul_f32 v[38:39], v[40:41], v[42:43]
	v_add_f32_e32 v40, 1.0, v44
	v_add_f32_e32 v41, 1.0, v45
	v_rcp_f32_e32 v40, v40
	v_rcp_f32_e32 v41, v41
	v_cvt_pk_bf16_f32 v48, v38, v39
	v_mov_b32_e32 v38, v34
	v_mov_b32_e32 v39, v36
	v_pk_mul_f32 v[38:39], v[38:39], v[40:41]
	v_mov_b32_e32 v36, v35
	v_pk_mul_f32 v[34:35], v[36:37], v[38:39]
	v_mul_f32_e32 v36, 0xbfb8aa3b, v30
	v_mul_f32_e32 v37, 0xbfb8aa3b, v32
	v_or_b32_e32 v54, 0x50, v110
	v_exp_f32_e32 v36, v36
	v_exp_f32_e32 v37, v37
	v_cvt_pk_bf16_f32 v49, v34, v35
	v_mad_i64_i32 v[34:35], s[16:17], v54, s38, v[106:107]
	v_lshl_add_u64 v[34:35], v[34:35], 0, v[108:109]
	v_lshl_add_u64 v[34:35], v[34:35], 0, v[190:191]
	global_store_dwordx4 v[34:35], v[46:49], off
	v_add_f32_e32 v34, 1.0, v36
	v_add_f32_e32 v35, 1.0, v37
	v_rcp_f32_e32 v34, v34
	v_rcp_f32_e32 v35, v35
	v_mov_b32_e32 v36, v30
	v_mov_b32_e32 v37, v32
	v_mul_f32_e32 v30, 0xbfb8aa3b, v26
	v_pk_mul_f32 v[34:35], v[36:37], v[34:35]
	v_exp_f32_e32 v36, v30
	v_mul_f32_e32 v30, 0xbfb8aa3b, v28
	v_exp_f32_e32 v37, v30
	v_mov_b32_e32 v32, v31
	v_pk_mul_f32 v[30:31], v[32:33], v[34:35]
	v_add_f32_e32 v32, 1.0, v36
	v_add_f32_e32 v33, 1.0, v37
	v_rcp_f32_e32 v32, v32
	v_rcp_f32_e32 v33, v33
	v_mov_b32_e32 v34, v26
	v_mul_f32_e32 v26, 0xbfb8aa3b, v22
	v_cvt_pk_bf16_f32 v30, v30, v31
	v_mov_b32_e32 v35, v28
	v_exp_f32_e32 v31, v26
	v_mul_f32_e32 v26, 0xbfb8aa3b, v24
	v_pk_mul_f32 v[32:33], v[34:35], v[32:33]
	v_exp_f32_e32 v34, v26
	v_mov_b32_e32 v28, v27
	v_pk_mul_f32 v[26:27], v[28:29], v[32:33]
	v_add_f32_e32 v28, 1.0, v31
	v_add_f32_e32 v29, 1.0, v34
	v_rcp_f32_e32 v28, v28
	v_rcp_f32_e32 v29, v29
	v_cvt_pk_bf16_f32 v31, v26, v27
	v_mov_b32_e32 v26, v22
	v_mov_b32_e32 v27, v24
	v_mul_f32_e32 v22, 0xbfb8aa3b, v18
	v_pk_mul_f32 v[26:27], v[26:27], v[28:29]
	v_exp_f32_e32 v28, v22
	v_mul_f32_e32 v22, 0xbfb8aa3b, v20
	v_exp_f32_e32 v29, v22
	v_mov_b32_e32 v24, v23
	v_pk_mul_f32 v[22:23], v[24:25], v[26:27]
	v_add_f32_e32 v24, 1.0, v28
	v_add_f32_e32 v25, 1.0, v29
	v_rcp_f32_e32 v24, v24
	v_rcp_f32_e32 v25, v25
	v_cvt_pk_bf16_f32 v32, v22, v23
	v_mov_b32_e32 v22, v18
	v_mov_b32_e32 v23, v20
	v_pk_mul_f32 v[22:23], v[22:23], v[24:25]
	v_mov_b32_e32 v20, v19
	v_pk_mul_f32 v[18:19], v[20:21], v[22:23]
	v_mul_f32_e32 v20, 0xbfb8aa3b, v14
	v_mul_f32_e32 v21, 0xbfb8aa3b, v16
	v_or_b32_e32 v38, 0x60, v110
	v_exp_f32_e32 v20, v20
	v_exp_f32_e32 v21, v21
	v_cvt_pk_bf16_f32 v33, v18, v19
	v_mad_i64_i32 v[18:19], s[16:17], v38, s38, v[106:107]
	v_lshl_add_u64 v[18:19], v[18:19], 0, v[108:109]
	v_lshl_add_u64 v[18:19], v[18:19], 0, v[190:191]
	global_store_dwordx4 v[18:19], v[30:33], off
	v_add_f32_e32 v18, 1.0, v20
	v_add_f32_e32 v19, 1.0, v21
	v_rcp_f32_e32 v18, v18
	v_rcp_f32_e32 v19, v19
	v_mov_b32_e32 v20, v14
	v_mov_b32_e32 v21, v16
	v_mul_f32_e32 v14, 0xbfb8aa3b, v10
	v_pk_mul_f32 v[18:19], v[20:21], v[18:19]
	v_exp_f32_e32 v20, v14
	v_mul_f32_e32 v14, 0xbfb8aa3b, v12
	v_exp_f32_e32 v21, v14
	v_mov_b32_e32 v16, v15
	v_pk_mul_f32 v[14:15], v[16:17], v[18:19]
	v_add_f32_e32 v16, 1.0, v20
	v_add_f32_e32 v17, 1.0, v21
	v_rcp_f32_e32 v16, v16
	v_rcp_f32_e32 v17, v17
	v_mov_b32_e32 v18, v10
	v_mul_f32_e32 v10, 0xbfb8aa3b, v6
	v_cvt_pk_bf16_f32 v14, v14, v15
	v_mov_b32_e32 v19, v12
	v_exp_f32_e32 v15, v10
	v_mul_f32_e32 v10, 0xbfb8aa3b, v8
	v_pk_mul_f32 v[16:17], v[18:19], v[16:17]
	v_exp_f32_e32 v18, v10
	v_mov_b32_e32 v12, v11
	v_pk_mul_f32 v[10:11], v[12:13], v[16:17]
	v_add_f32_e32 v12, 1.0, v15
	v_add_f32_e32 v13, 1.0, v18
	v_rcp_f32_e32 v12, v12
	v_rcp_f32_e32 v13, v13
	v_cvt_pk_bf16_f32 v15, v10, v11
	v_mov_b32_e32 v10, v6
	v_mov_b32_e32 v11, v8
	v_mul_f32_e32 v6, 0xbfb8aa3b, v2
	v_pk_mul_f32 v[10:11], v[10:11], v[12:13]
	v_exp_f32_e32 v12, v6
	v_mul_f32_e32 v6, 0xbfb8aa3b, v4
	v_exp_f32_e32 v13, v6
	v_mov_b32_e32 v8, v7
	v_pk_mul_f32 v[6:7], v[8:9], v[10:11]
	v_add_f32_e32 v8, 1.0, v12
	v_add_f32_e32 v9, 1.0, v13
	v_rcp_f32_e32 v8, v8
	v_rcp_f32_e32 v9, v9
	v_cvt_pk_bf16_f32 v16, v6, v7
	v_mov_b32_e32 v6, v2
	v_mov_b32_e32 v7, v4
	v_pk_mul_f32 v[6:7], v[6:7], v[8:9]
	v_mov_b32_e32 v4, v3
	v_or_b32_e32 v22, 0x70, v110
	v_pk_mul_f32 v[2:3], v[4:5], v[6:7]
	s_add_i32 s37, s37, s30
	v_cvt_pk_bf16_f32 v17, v2, v3
	v_mad_i64_i32 v[2:3], s[16:17], v22, s38, v[106:107]
	v_lshl_add_u64 v[2:3], v[2:3], 0, v[108:109]
	s_cmp_gt_i32 s37, 31
	v_lshl_add_u64 v[2:3], v[2:3], 0, v[190:191]
	s_cselect_b64 s[16:17], -1, 0
	v_readlane_b32 s53, v253, 41
	v_readlane_b32 s56, v253, 44
	v_readlane_b32 s57, v253, 45
	v_readlane_b32 s58, v253, 46
	v_readlane_b32 s59, v253, 47
	v_readlane_b32 s60, v253, 48
	v_readlane_b32 s61, v253, 49
	v_readlane_b32 s62, v253, 50
	v_readlane_b32 s63, v253, 51
	v_readlane_b32 s64, v253, 52
	v_readlane_b32 s65, v253, 53
	v_readlane_b32 s66, v253, 54
	v_readlane_b32 s67, v253, 55
	global_store_dwordx4 v[2:3], v[14:17], off
	s_branch .LBB0_68

; #define MFMA16(a, b, c) __builtin_amdgcn_mfma_f32_16x16x32_bf16((a), (b), (c), 0, 0, 0)
;     ...
;   for (int kt = 0; kt < nk; ++kt) {
;     const int buf = kt & 1;
;     const char* cA = smem + buf * STAGE + (wm * 32 * MI + r16) * 128;
;     const char* cB = smem + buf * STAGE + 32768 + (wn * 64 + r16) * 128;
; #pragma unroll
;     for (int k2 = 0; k2 < 2; ++k2) {
;       if (k2 == 1 && kt + 1 < nk) STAGE_TILE(buf ^ 1, (kt + 1) * 64)
;       const int po = ((4 * k2 + q4) ^ swz) * 16;
;       bf16x8 bf[4];
; #pragma unroll
;       for (int nt = 0; nt < 4; ++nt) bf[nt] = *(const bf16x8*)(cB + nt * 16 * 128 + po);
;       bf16x8 afc = *(const bf16x8*)(cA + po);
; #pragma unroll
;       for (int a = 0; a < MT; ++a) {
;         bf16x8 afn = afc;
;         if (a + 1 < MT) afn = *(const bf16x8*)(cA + (a + 1) * 16 * 128 + po);
;         __builtin_amdgcn_sched_barrier(0);
; #pragma unroll
;         for (int nt = 0; nt < 4; ++nt) acc[a][nt] = MFMA16(bf[nt], afc, acc[a][nt]);
;         __builtin_amdgcn_sched_barrier(0);
;         afc = afn;
;       }
;     }
;     asm volatile("s_waitcnt vmcnt(0)" ::: "memory");
;     __syncthreads();
;   }
.LBB0_107:
	s_and_b32 s46, s45, 0x10000
	s_add_i32 s47, s46, 0
	s_xor_b32 s46, s46, 0x10000
	v_add_u32_e32 v174, s47, v147
	v_add_u32_e32 v162, v174, v146
	v_add_u32_e32 v149, s47, v148
	ds_read_b128 v[150:153], v162 offset:32768
	ds_read_b128 v[154:157], v162 offset:34816
	ds_read_b128 v[158:161], v162 offset:36864
	ds_read_b128 v[162:165], v162 offset:38912
	v_add_u32_e32 v175, v149, v146
	ds_read_b128 v[166:169], v175
	ds_read_b128 v[170:173], v175 offset:2048
	s_waitcnt lgkmcnt(1)
	v_mfma_f32_16x16x32_bf16 v[126:129], v[150:153], v[166:169], v[126:129]
	v_readfirstlane_b32 s47, v145
	v_mfma_f32_16x16x32_bf16 v[122:125], v[154:157], v[166:169], v[122:125]
	s_nop 0
	v_mfma_f32_16x16x32_bf16 v[118:121], v[158:161], v[166:169], v[118:121]
	s_add_u32 s47, s47, s46
	v_mfma_f32_16x16x32_bf16 v[114:117], v[162:165], v[166:169], v[114:117]
	ds_read_b128 v[166:169], v175 offset:4096
	s_waitcnt lgkmcnt(1)
	v_mfma_f32_16x16x32_bf16 v[110:113], v[150:153], v[170:173], v[110:113]
	s_add_u32 m0, s47, 0x0
	v_mfma_f32_16x16x32_bf16 v[106:109], v[154:157], v[170:173], v[106:109]
	global_load_lds_dwordx4 v176, s[100:101]
	v_mfma_f32_16x16x32_bf16 v[102:105], v[158:161], v[170:173], v[102:105]
	s_add_u32 m0, s47, 0x2000
	v_mfma_f32_16x16x32_bf16 v[98:101], v[162:165], v[170:173], v[98:101]
	ds_read_b128 v[170:173], v175 offset:6144
	s_waitcnt lgkmcnt(1)
	v_mfma_f32_16x16x32_bf16 v[94:97], v[150:153], v[166:169], v[94:97]
	global_load_lds_dwordx4 v177, s[100:101]
	v_mfma_f32_16x16x32_bf16 v[90:93], v[154:157], v[166:169], v[90:93]
	s_add_u32 m0, s47, 0x4000
	v_mfma_f32_16x16x32_bf16 v[86:89], v[158:161], v[166:169], v[86:89]
	global_load_lds_dwordx4 v178, s[100:101]
	v_mfma_f32_16x16x32_bf16 v[82:85], v[162:165], v[166:169], v[82:85]
	ds_read_b128 v[166:169], v175 offset:8192
	s_waitcnt lgkmcnt(1)
	v_mfma_f32_16x16x32_bf16 v[78:81], v[150:153], v[170:173], v[78:81]
	s_add_u32 m0, s47, 0x6000
	v_mfma_f32_16x16x32_bf16 v[74:77], v[154:157], v[170:173], v[74:77]
	global_load_lds_dwordx4 v179, s[100:101]
	v_mfma_f32_16x16x32_bf16 v[70:73], v[158:161], v[170:173], v[70:73]
	s_add_u32 m0, s47, 0x8000
	v_mfma_f32_16x16x32_bf16 v[66:69], v[162:165], v[170:173], v[66:69]
	ds_read_b128 v[170:173], v175 offset:10240
	s_waitcnt lgkmcnt(1)
	v_mfma_f32_16x16x32_bf16 v[62:65], v[150:153], v[166:169], v[62:65]
	global_load_lds_dwordx4 v180, s[100:101]
	v_mfma_f32_16x16x32_bf16 v[58:61], v[154:157], v[166:169], v[58:61]
	s_add_u32 m0, s47, 0xa000
	v_mfma_f32_16x16x32_bf16 v[54:57], v[158:161], v[166:169], v[54:57]
	global_load_lds_dwordx4 v181, s[100:101]
	v_mfma_f32_16x16x32_bf16 v[50:53], v[162:165], v[166:169], v[50:53]
	ds_read_b128 v[166:169], v175 offset:12288
	s_waitcnt lgkmcnt(1)
	v_mfma_f32_16x16x32_bf16 v[46:49], v[150:153], v[170:173], v[46:49]
	s_add_u32 m0, s47, 0xc000
	v_mfma_f32_16x16x32_bf16 v[42:45], v[154:157], v[170:173], v[42:45]
	global_load_lds_dwordx4 v182, s[100:101]
	v_mfma_f32_16x16x32_bf16 v[38:41], v[158:161], v[170:173], v[38:41]
	s_add_u32 m0, s47, 0xe000
	v_mfma_f32_16x16x32_bf16 v[34:37], v[162:165], v[170:173], v[34:37]
	ds_read_b128 v[170:173], v175 offset:14336
	s_waitcnt lgkmcnt(1)
	v_mfma_f32_16x16x32_bf16 v[30:33], v[150:153], v[166:169], v[30:33]
	global_load_lds_dwordx4 v183, s[100:101]
	v_mfma_f32_16x16x32_bf16 v[26:29], v[154:157], v[166:169], v[26:29]
	v_mfma_f32_16x16x32_bf16 v[22:25], v[158:161], v[166:169], v[22:25]
	v_mfma_f32_16x16x32_bf16 v[18:21], v[162:165], v[166:169], v[18:21]
	s_waitcnt lgkmcnt(0)
	v_mfma_f32_16x16x32_bf16 v[14:17], v[150:153], v[170:173], v[14:17]
	v_mfma_f32_16x16x32_bf16 v[10:13], v[154:157], v[170:173], v[10:13]
	v_mfma_f32_16x16x32_bf16 v[6:9], v[158:161], v[170:173], v[6:9]
	v_mfma_f32_16x16x32_bf16 v[2:5], v[162:165], v[170:173], v[2:5]
	v_add_u32_e32 v162, v174, v144
	ds_read_b128 v[150:153], v162 offset:32768
	ds_read_b128 v[154:157], v162 offset:34816
	ds_read_b128 v[158:161], v162 offset:36864
	ds_read_b128 v[162:165], v162 offset:38912
	v_add_u32_e32 v149, v149, v144
	ds_read_b128 v[166:169], v149
	ds_read_b128 v[170:173], v149 offset:2048
	s_waitcnt lgkmcnt(0)
	v_mfma_f32_16x16x32_bf16 v[126:129], v[150:153], v[166:169], v[126:129]
	v_mfma_f32_16x16x32_bf16 v[122:125], v[154:157], v[166:169], v[122:125]
	v_mfma_f32_16x16x32_bf16 v[118:121], v[158:161], v[166:169], v[118:121]
	v_mfma_f32_16x16x32_bf16 v[114:117], v[162:165], v[166:169], v[114:117]
	ds_read_b128 v[166:169], v149 offset:4096
	v_mfma_f32_16x16x32_bf16 v[110:113], v[150:153], v[170:173], v[110:113]
	v_mfma_f32_16x16x32_bf16 v[106:109], v[154:157], v[170:173], v[106:109]
	v_mfma_f32_16x16x32_bf16 v[102:105], v[158:161], v[170:173], v[102:105]
	v_mfma_f32_16x16x32_bf16 v[98:101], v[162:165], v[170:173], v[98:101]
	ds_read_b128 v[170:173], v149 offset:6144
	s_waitcnt lgkmcnt(0)
	v_mfma_f32_16x16x32_bf16 v[94:97], v[150:153], v[166:169], v[94:97]
	v_mfma_f32_16x16x32_bf16 v[90:93], v[154:157], v[166:169], v[90:93]
	v_mfma_f32_16x16x32_bf16 v[86:89], v[158:161], v[166:169], v[86:89]
	v_mfma_f32_16x16x32_bf16 v[82:85], v[162:165], v[166:169], v[82:85]
	ds_read_b128 v[166:169], v149 offset:8192
	v_mfma_f32_16x16x32_bf16 v[78:81], v[150:153], v[170:173], v[78:81]
	v_mfma_f32_16x16x32_bf16 v[74:77], v[154:157], v[170:173], v[74:77]
	v_mfma_f32_16x16x32_bf16 v[70:73], v[158:161], v[170:173], v[70:73]
	v_mfma_f32_16x16x32_bf16 v[66:69], v[162:165], v[170:173], v[66:69]
	ds_read_b128 v[170:173], v149 offset:10240
	s_waitcnt lgkmcnt(0)
	v_mfma_f32_16x16x32_bf16 v[62:65], v[150:153], v[166:169], v[62:65]
	v_mfma_f32_16x16x32_bf16 v[58:61], v[154:157], v[166:169], v[58:61]
	v_mfma_f32_16x16x32_bf16 v[54:57], v[158:161], v[166:169], v[54:57]
	v_mfma_f32_16x16x32_bf16 v[50:53], v[162:165], v[166:169], v[50:53]
	ds_read_b128 v[166:169], v149 offset:12288
	v_mfma_f32_16x16x32_bf16 v[46:49], v[150:153], v[170:173], v[46:49]
	v_mfma_f32_16x16x32_bf16 v[42:45], v[154:157], v[170:173], v[42:45]
	v_mfma_f32_16x16x32_bf16 v[38:41], v[158:161], v[170:173], v[38:41]
	v_mfma_f32_16x16x32_bf16 v[34:37], v[162:165], v[170:173], v[34:37]
	ds_read_b128 v[170:173], v149 offset:14336
	s_waitcnt lgkmcnt(0)
	v_mfma_f32_16x16x32_bf16 v[30:33], v[150:153], v[166:169], v[30:33]
	v_mfma_f32_16x16x32_bf16 v[26:29], v[154:157], v[166:169], v[26:29]
	v_mfma_f32_16x16x32_bf16 v[22:25], v[158:161], v[166:169], v[22:25]
	v_mfma_f32_16x16x32_bf16 v[18:21], v[162:165], v[166:169], v[18:21]
	v_mfma_f32_16x16x32_bf16 v[14:17], v[150:153], v[170:173], v[14:17]
	v_mfma_f32_16x16x32_bf16 v[10:13], v[154:157], v[170:173], v[10:13]
	v_mfma_f32_16x16x32_bf16 v[6:9], v[158:161], v[170:173], v[6:9]
	v_mfma_f32_16x16x32_bf16 v[2:5], v[162:165], v[170:173], v[2:5]
	s_waitcnt vmcnt(0)
	s_add_u32 s100, s100, 0x80
	s_addc_u32 s101, s101, 0
	s_add_u32 s22, s22, 0x80
	s_addc_u32 s23, s23, 0
	s_add_i32 s45, s45, 0x10000
	s_cmpk_eq_i32 s22, 0x780
	s_waitcnt vmcnt(0)
	s_barrier
	s_cbranch_scc0 .LBB0_107
	s_branch .LBB0_99

; #define MFMA16(a, b, c) __builtin_amdgcn_mfma_f32_16x16x32_bf16((a), (b), (c), 0, 0, 0)
;     ...
;   for (int kt = 0; kt < nk; ++kt) {
;     const int buf = kt & 1;
;     const char* cA = smem + buf * STAGE + (wm * 32 * MI + r16) * 128;
;     const char* cB = smem + buf * STAGE + 32768 + (wn * 64 + r16) * 128;
; #pragma unroll
;     for (int k2 = 0; k2 < 2; ++k2) {
;       if (k2 == 1 && kt + 1 < nk) STAGE_TILE(buf ^ 1, (kt + 1) * 64)
;       const int po = ((4 * k2 + q4) ^ swz) * 16;
;       bf16x8 bf[4];
; #pragma unroll
;       for (int nt = 0; nt < 4; ++nt) bf[nt] = *(const bf16x8*)(cB + nt * 16 * 128 + po);
;       bf16x8 afc = *(const bf16x8*)(cA + po);
; #pragma unroll
;       for (int a = 0; a < MT; ++a) {
;         bf16x8 afn = afc;
;         if (a + 1 < MT) afn = *(const bf16x8*)(cA + (a + 1) * 16 * 128 + po);
;         __builtin_amdgcn_sched_barrier(0);
; #pragma unroll
;         for (int nt = 0; nt < 4; ++nt) acc[a][nt] = MFMA16(bf[nt], afc, acc[a][nt]);
;         __builtin_amdgcn_sched_barrier(0);
;         afc = afn;
;       }
;     }
;     asm volatile("s_waitcnt vmcnt(0)" ::: "memory");
;     __syncthreads();
;   }
.LBB0_565:
	s_and_b32 s6, s5, 0x10000
	s_add_i32 s7, s6, 0
	v_add_u32_e32 v190, s7, v146
	v_add_u32_e32 v164, v190, v145
	v_add_u32_e32 v163, s7, v147
	ds_read_b128 v[148:151], v164 offset:32768
	ds_read_b128 v[152:155], v164 offset:34816
	ds_read_b128 v[156:159], v164 offset:36864
	ds_read_b128 v[164:167], v164 offset:38912
	v_add_u32_e32 v202, v163, v145
	ds_read_b128 v[168:171], v202
	ds_read_b128 v[172:175], v202 offset:2048
	s_xor_b32 s6, s6, 0x10000
	s_waitcnt lgkmcnt(1)
	v_mfma_f32_16x16x32_bf16 v[126:129], v[148:151], v[168:171], v[126:129]
	v_readfirstlane_b32 s7, v144
	v_mfma_f32_16x16x32_bf16 v[122:125], v[152:155], v[168:171], v[122:125]
	s_nop 0
	v_mfma_f32_16x16x32_bf16 v[118:121], v[156:159], v[168:171], v[118:121]
	s_add_u32 s7, s7, s6
	v_mfma_f32_16x16x32_bf16 v[114:117], v[164:167], v[168:171], v[114:117]
	ds_read_b128 v[168:171], v202 offset:4096
	s_waitcnt lgkmcnt(1)
	v_mfma_f32_16x16x32_bf16 v[110:113], v[148:151], v[172:175], v[110:113]
	s_add_u32 m0, s7, 0x0
	v_mfma_f32_16x16x32_bf16 v[106:109], v[152:155], v[172:175], v[106:109]
	global_load_lds_dwordx4 v176, s[100:101]
	v_mfma_f32_16x16x32_bf16 v[102:105], v[156:159], v[172:175], v[102:105]
	s_add_u32 m0, s7, 0x2000
	v_mfma_f32_16x16x32_bf16 v[98:101], v[164:167], v[172:175], v[98:101]
	ds_read_b128 v[172:175], v202 offset:6144
	s_waitcnt lgkmcnt(1)
	v_mfma_f32_16x16x32_bf16 v[94:97], v[148:151], v[168:171], v[94:97]
	global_load_lds_dwordx4 v177, s[100:101]
	v_mfma_f32_16x16x32_bf16 v[90:93], v[152:155], v[168:171], v[90:93]
	s_add_u32 m0, s7, 0x4000
	v_mfma_f32_16x16x32_bf16 v[86:89], v[156:159], v[168:171], v[86:89]
	global_load_lds_dwordx4 v178, s[100:101]
	v_mfma_f32_16x16x32_bf16 v[82:85], v[164:167], v[168:171], v[82:85]
	ds_read_b128 v[168:171], v202 offset:8192
	s_waitcnt lgkmcnt(1)
	v_mfma_f32_16x16x32_bf16 v[78:81], v[148:151], v[172:175], v[78:81]
	s_add_u32 m0, s7, 0x6000
	v_mfma_f32_16x16x32_bf16 v[74:77], v[152:155], v[172:175], v[74:77]
	global_load_lds_dwordx4 v179, s[100:101]
	v_mfma_f32_16x16x32_bf16 v[70:73], v[156:159], v[172:175], v[70:73]
	s_add_u32 m0, s7, 0x8000
	v_mfma_f32_16x16x32_bf16 v[66:69], v[164:167], v[172:175], v[66:69]
	ds_read_b128 v[172:175], v202 offset:10240
	s_waitcnt lgkmcnt(1)
	v_mfma_f32_16x16x32_bf16 v[62:65], v[148:151], v[168:171], v[62:65]
	global_load_lds_dwordx4 v180, s[100:101]
	v_mfma_f32_16x16x32_bf16 v[58:61], v[152:155], v[168:171], v[58:61]
	s_add_u32 m0, s7, 0xa000
	v_mfma_f32_16x16x32_bf16 v[54:57], v[156:159], v[168:171], v[54:57]
	global_load_lds_dwordx4 v181, s[100:101]
	v_mfma_f32_16x16x32_bf16 v[50:53], v[164:167], v[168:171], v[50:53]
	ds_read_b128 v[168:171], v202 offset:12288
	s_waitcnt lgkmcnt(1)
	v_mfma_f32_16x16x32_bf16 v[46:49], v[148:151], v[172:175], v[46:49]
	s_add_u32 m0, s7, 0xc000
	v_mfma_f32_16x16x32_bf16 v[42:45], v[152:155], v[172:175], v[42:45]
	global_load_lds_dwordx4 v182, s[100:101]
	v_mfma_f32_16x16x32_bf16 v[38:41], v[156:159], v[172:175], v[38:41]
	s_add_u32 m0, s7, 0xe000
	v_mfma_f32_16x16x32_bf16 v[34:37], v[164:167], v[172:175], v[34:37]
	ds_read_b128 v[172:175], v202 offset:14336
	s_waitcnt lgkmcnt(1)
	v_mfma_f32_16x16x32_bf16 v[30:33], v[148:151], v[168:171], v[30:33]
	global_load_lds_dwordx4 v183, s[100:101]
	v_mfma_f32_16x16x32_bf16 v[26:29], v[152:155], v[168:171], v[26:29]
	v_mfma_f32_16x16x32_bf16 v[22:25], v[156:159], v[168:171], v[22:25]
	v_mfma_f32_16x16x32_bf16 v[18:21], v[164:167], v[168:171], v[18:21]
	s_waitcnt lgkmcnt(0)
	v_mfma_f32_16x16x32_bf16 v[14:17], v[148:151], v[172:175], v[14:17]
	v_mfma_f32_16x16x32_bf16 v[10:13], v[152:155], v[172:175], v[10:13]
	v_mfma_f32_16x16x32_bf16 v[6:9], v[156:159], v[172:175], v[6:9]
	v_mfma_f32_16x16x32_bf16 v[2:5], v[164:167], v[172:175], v[2:5]
	v_add_u32_e32 v160, v190, v143
	ds_read_b128 v[148:151], v160 offset:32768
	ds_read_b128 v[152:155], v160 offset:34816
	ds_read_b128 v[156:159], v160 offset:36864
	ds_read_b128 v[164:167], v160 offset:38912
	v_add_u32_e32 v160, v163, v143
	ds_read_b128 v[168:171], v160
	ds_read_b128 v[172:175], v160 offset:2048
	s_waitcnt lgkmcnt(0)
	v_mfma_f32_16x16x32_bf16 v[126:129], v[148:151], v[168:171], v[126:129]
	v_mfma_f32_16x16x32_bf16 v[122:125], v[152:155], v[168:171], v[122:125]
	v_mfma_f32_16x16x32_bf16 v[118:121], v[156:159], v[168:171], v[118:121]
	v_mfma_f32_16x16x32_bf16 v[114:117], v[164:167], v[168:171], v[114:117]
	ds_read_b128 v[168:171], v160 offset:4096
	v_mfma_f32_16x16x32_bf16 v[110:113], v[148:151], v[172:175], v[110:113]
	v_mfma_f32_16x16x32_bf16 v[106:109], v[152:155], v[172:175], v[106:109]
	v_mfma_f32_16x16x32_bf16 v[102:105], v[156:159], v[172:175], v[102:105]
	v_mfma_f32_16x16x32_bf16 v[98:101], v[164:167], v[172:175], v[98:101]
	ds_read_b128 v[172:175], v160 offset:6144
	s_waitcnt lgkmcnt(0)
	v_mfma_f32_16x16x32_bf16 v[94:97], v[148:151], v[168:171], v[94:97]
	v_mfma_f32_16x16x32_bf16 v[90:93], v[152:155], v[168:171], v[90:93]
	v_mfma_f32_16x16x32_bf16 v[86:89], v[156:159], v[168:171], v[86:89]
	v_mfma_f32_16x16x32_bf16 v[82:85], v[164:167], v[168:171], v[82:85]
	ds_read_b128 v[168:171], v160 offset:8192
	v_mfma_f32_16x16x32_bf16 v[78:81], v[148:151], v[172:175], v[78:81]
	v_mfma_f32_16x16x32_bf16 v[74:77], v[152:155], v[172:175], v[74:77]
	v_mfma_f32_16x16x32_bf16 v[70:73], v[156:159], v[172:175], v[70:73]
	v_mfma_f32_16x16x32_bf16 v[66:69], v[164:167], v[172:175], v[66:69]
	ds_read_b128 v[172:175], v160 offset:10240
	s_waitcnt lgkmcnt(0)
	v_mfma_f32_16x16x32_bf16 v[62:65], v[148:151], v[168:171], v[62:65]
	v_mfma_f32_16x16x32_bf16 v[58:61], v[152:155], v[168:171], v[58:61]
	v_mfma_f32_16x16x32_bf16 v[54:57], v[156:159], v[168:171], v[54:57]
	v_mfma_f32_16x16x32_bf16 v[50:53], v[164:167], v[168:171], v[50:53]
	ds_read_b128 v[168:171], v160 offset:12288
	v_mfma_f32_16x16x32_bf16 v[46:49], v[148:151], v[172:175], v[46:49]
	v_mfma_f32_16x16x32_bf16 v[42:45], v[152:155], v[172:175], v[42:45]
	v_mfma_f32_16x16x32_bf16 v[38:41], v[156:159], v[172:175], v[38:41]
	v_mfma_f32_16x16x32_bf16 v[34:37], v[164:167], v[172:175], v[34:37]
	ds_read_b128 v[172:175], v160 offset:14336
	s_waitcnt lgkmcnt(0)
	v_mfma_f32_16x16x32_bf16 v[30:33], v[148:151], v[168:171], v[30:33]
	v_mfma_f32_16x16x32_bf16 v[26:29], v[152:155], v[168:171], v[26:29]
	v_mfma_f32_16x16x32_bf16 v[22:25], v[156:159], v[168:171], v[22:25]
	v_mfma_f32_16x16x32_bf16 v[18:21], v[164:167], v[168:171], v[18:21]
	v_mfma_f32_16x16x32_bf16 v[14:17], v[148:151], v[172:175], v[14:17]
	v_mfma_f32_16x16x32_bf16 v[10:13], v[152:155], v[172:175], v[10:13]
	v_mfma_f32_16x16x32_bf16 v[6:9], v[156:159], v[172:175], v[6:9]
	v_mfma_f32_16x16x32_bf16 v[2:5], v[164:167], v[172:175], v[2:5]
	s_waitcnt vmcnt(0)
	s_add_u32 s100, s100, 0x80
	s_addc_u32 s101, s101, 0
	s_add_u32 s2, s2, 0x80
	s_addc_u32 s3, s3, 0
	s_add_i32 s5, s5, 0x10000
	s_cmpk_eq_i32 s2, 0x780
	s_waitcnt vmcnt(0)
	s_barrier
; #define MFMA16(a, b, c) __builtin_amdgcn_mfma_f32_16x16x32_bf16((a), (b), (c), 0, 0, 0)
;     ...
;   for (int kt = 0; kt < nk; ++kt) {
;     const int buf = kt & 1;
;     const char* cA = smem + buf * STAGE + (wm * 32 * MI + r16) * 128;
;     const char* cB = smem + buf * STAGE + 32768 + (wn * 64 + r16) * 128;
; #pragma unroll
;     for (int k2 = 0; k2 < 2; ++k2) {
;       if (k2 == 1 && kt + 1 < nk) STAGE_TILE(buf ^ 1, (kt + 1) * 64)
;       const int po = ((4 * k2 + q4) ^ swz) * 16;
;       bf16x8 bf[4];
; #pragma unroll
;       for (int nt = 0; nt < 4; ++nt) bf[nt] = *(const bf16x8*)(cB + nt * 16 * 128 + po);
;       bf16x8 afc = *(const bf16x8*)(cA + po);
; #pragma unroll
;       for (int a = 0; a < MT; ++a) {
;         bf16x8 afn = afc;
;         if (a + 1 < MT) afn = *(const bf16x8*)(cA + (a + 1) * 16 * 128 + po);
;         __builtin_amdgcn_sched_barrier(0);
; #pragma unroll
;         for (int nt = 0; nt < 4; ++nt) acc[a][nt] = MFMA16(bf[nt], afc, acc[a][nt]);
;         __builtin_amdgcn_sched_barrier(0);
;         afc = afn;
;       }
;     }
; DI void phase_win(char* smem, const Params& p, int layer) {
;     ...
;   auto ep = [&](int row, int cbw, int q4, const f32x4& c0, const f32x4& c1, const f32x4& c2, const f32x4& c3) {
;     if (cbw > 2432) return;
;     const int b = row / TT, t = row - b * TT;
;     const bool lat = t >= CTXL;
;     const int pos = t - CTXL;
;     float v[16] = {c0[0], c0[1], c0[2], c0[3], c1[0], c1[1], c1[2], c1[3], c2[0], c2[1], c2[2], c2[3], c3[0], c3[1], c3[2], c3[3]};
;     if (cbw >= 640 && cbw < 768) {
	s_cbranch_scc0 .LBB0_565
	s_add_i32 s2, 0, 0x10000
	v_add_u32_e32 v138, s2, v147
	v_readlane_b32 s2, v254, 18
	s_nop 1
	v_add_u32_e32 v139, s2, v146
	v_add_u32_e32 v144, v139, v145
	ds_read_b128 v[130:133], v144
	ds_read_b128 v[134:137], v144 offset:2048
	ds_read_b128 v[146:149], v144 offset:4096
	ds_read_b128 v[150:153], v144 offset:6144
	v_add_u32_e32 v144, v138, v145
	ds_read_b128 v[154:157], v144
	ds_read_b128 v[158:161], v144 offset:2048
	s_waitcnt lgkmcnt(1)
	v_mfma_f32_16x16x32_bf16 v[122:125], v[134:137], v[154:157], v[122:125]
	v_mfma_f32_16x16x32_bf16 v[118:121], v[146:149], v[154:157], v[118:121]
	v_mfma_f32_16x16x32_bf16 v[114:117], v[150:153], v[154:157], v[114:117]
	v_mfma_f32_16x16x32_bf16 v[126:129], v[130:133], v[154:157], v[126:129]
	ds_read_b128 v[154:157], v144 offset:4096
	s_waitcnt lgkmcnt(1)
	v_mfma_f32_16x16x32_bf16 v[110:113], v[130:133], v[158:161], v[110:113]
	v_mfma_f32_16x16x32_bf16 v[106:109], v[134:137], v[158:161], v[106:109]
	v_mfma_f32_16x16x32_bf16 v[102:105], v[146:149], v[158:161], v[102:105]
	v_mfma_f32_16x16x32_bf16 v[98:101], v[150:153], v[158:161], v[98:101]
	ds_read_b128 v[158:161], v144 offset:6144
	s_waitcnt lgkmcnt(1)
	v_mfma_f32_16x16x32_bf16 v[94:97], v[130:133], v[154:157], v[94:97]
	v_mfma_f32_16x16x32_bf16 v[90:93], v[134:137], v[154:157], v[90:93]
	v_mfma_f32_16x16x32_bf16 v[86:89], v[146:149], v[154:157], v[86:89]
	v_mfma_f32_16x16x32_bf16 v[82:85], v[150:153], v[154:157], v[82:85]
	ds_read_b128 v[154:157], v144 offset:8192
	s_waitcnt lgkmcnt(1)
	v_mfma_f32_16x16x32_bf16 v[78:81], v[130:133], v[158:161], v[78:81]
	v_mfma_f32_16x16x32_bf16 v[74:77], v[134:137], v[158:161], v[74:77]
	v_mfma_f32_16x16x32_bf16 v[70:73], v[146:149], v[158:161], v[70:73]
	v_mfma_f32_16x16x32_bf16 v[66:69], v[150:153], v[158:161], v[66:69]
	ds_read_b128 v[158:161], v144 offset:10240
	s_waitcnt lgkmcnt(1)
	v_mfma_f32_16x16x32_bf16 v[62:65], v[130:133], v[154:157], v[62:65]
	v_mfma_f32_16x16x32_bf16 v[58:61], v[134:137], v[154:157], v[58:61]
	v_mfma_f32_16x16x32_bf16 v[54:57], v[146:149], v[154:157], v[54:57]
	v_mfma_f32_16x16x32_bf16 v[50:53], v[150:153], v[154:157], v[50:53]
	ds_read_b128 v[154:157], v144 offset:12288
	s_waitcnt lgkmcnt(1)
	v_mfma_f32_16x16x32_bf16 v[46:49], v[130:133], v[158:161], v[46:49]
	v_mfma_f32_16x16x32_bf16 v[42:45], v[134:137], v[158:161], v[42:45]
	v_mfma_f32_16x16x32_bf16 v[38:41], v[146:149], v[158:161], v[38:41]
	v_mfma_f32_16x16x32_bf16 v[34:37], v[150:153], v[158:161], v[34:37]
	ds_read_b128 v[158:161], v144 offset:14336
	s_waitcnt lgkmcnt(1)
	v_mfma_f32_16x16x32_bf16 v[30:33], v[130:133], v[154:157], v[30:33]
	v_mfma_f32_16x16x32_bf16 v[26:29], v[134:137], v[154:157], v[26:29]
	v_mfma_f32_16x16x32_bf16 v[22:25], v[146:149], v[154:157], v[22:25]
	v_mfma_f32_16x16x32_bf16 v[18:21], v[150:153], v[154:157], v[18:21]
	s_waitcnt lgkmcnt(0)
	v_mfma_f32_16x16x32_bf16 v[14:17], v[130:133], v[158:161], v[14:17]
	v_mfma_f32_16x16x32_bf16 v[10:13], v[134:137], v[158:161], v[10:13]
	v_mfma_f32_16x16x32_bf16 v[6:9], v[146:149], v[158:161], v[6:9]
	v_mfma_f32_16x16x32_bf16 v[2:5], v[150:153], v[158:161], v[2:5]
	v_add_u32_e32 v130, v139, v143
	ds_read_b128 v[134:137], v130
	ds_read_b128 v[144:147], v130 offset:2048
	ds_read_b128 v[148:151], v130 offset:4096
	ds_read_b128 v[152:155], v130 offset:6144
	v_add_u32_e32 v138, v138, v143
	ds_read_b128 v[156:159], v138
	ds_read_b128 v[164:167], v138 offset:2048
	s_waitcnt lgkmcnt(1)
	v_mfma_f32_16x16x32_bf16 v[130:133], v[134:137], v[156:159], v[126:129]
	v_mfma_f32_16x16x32_bf16 v[122:125], v[144:147], v[156:159], v[122:125]
	v_mfma_f32_16x16x32_bf16 v[118:121], v[148:151], v[156:159], v[118:121]
	v_mfma_f32_16x16x32_bf16 v[114:117], v[152:155], v[156:159], v[114:117]
	ds_read_b128 v[126:129], v138 offset:4096
	s_waitcnt lgkmcnt(1)
	v_mfma_f32_16x16x32_bf16 v[110:113], v[134:137], v[164:167], v[110:113]
	v_mfma_f32_16x16x32_bf16 v[106:109], v[144:147], v[164:167], v[106:109]
	v_mfma_f32_16x16x32_bf16 v[102:105], v[148:151], v[164:167], v[102:105]
	v_mfma_f32_16x16x32_bf16 v[98:101], v[152:155], v[164:167], v[98:101]
	ds_read_b128 v[156:159], v138 offset:6144
	s_waitcnt lgkmcnt(1)
	v_mfma_f32_16x16x32_bf16 v[94:97], v[134:137], v[126:129], v[94:97]
	v_mfma_f32_16x16x32_bf16 v[90:93], v[144:147], v[126:129], v[90:93]
	v_mfma_f32_16x16x32_bf16 v[86:89], v[148:151], v[126:129], v[86:89]
	v_mfma_f32_16x16x32_bf16 v[82:85], v[152:155], v[126:129], v[82:85]
	ds_read_b128 v[126:129], v138 offset:8192
	s_waitcnt lgkmcnt(1)
	v_mfma_f32_16x16x32_bf16 v[78:81], v[134:137], v[156:159], v[78:81]
	v_mfma_f32_16x16x32_bf16 v[74:77], v[144:147], v[156:159], v[74:77]
	v_mfma_f32_16x16x32_bf16 v[70:73], v[148:151], v[156:159], v[70:73]
	v_mfma_f32_16x16x32_bf16 v[66:69], v[152:155], v[156:159], v[66:69]
	ds_read_b128 v[156:159], v138 offset:10240
	s_waitcnt lgkmcnt(1)
	v_mfma_f32_16x16x32_bf16 v[62:65], v[134:137], v[126:129], v[62:65]
	v_mfma_f32_16x16x32_bf16 v[58:61], v[144:147], v[126:129], v[58:61]
	v_mfma_f32_16x16x32_bf16 v[54:57], v[148:151], v[126:129], v[54:57]
	v_mfma_f32_16x16x32_bf16 v[50:53], v[152:155], v[126:129], v[50:53]
	ds_read_b128 v[126:129], v138 offset:12288
	s_waitcnt lgkmcnt(1)
	v_mfma_f32_16x16x32_bf16 v[46:49], v[134:137], v[156:159], v[46:49]
	v_mfma_f32_16x16x32_bf16 v[42:45], v[144:147], v[156:159], v[42:45]
	v_mfma_f32_16x16x32_bf16 v[38:41], v[148:151], v[156:159], v[38:41]
	v_mfma_f32_16x16x32_bf16 v[34:37], v[152:155], v[156:159], v[34:37]
	ds_read_b128 v[156:159], v138 offset:14336
	s_waitcnt lgkmcnt(1)
	v_mfma_f32_16x16x32_bf16 v[30:33], v[134:137], v[126:129], v[30:33]
	v_mfma_f32_16x16x32_bf16 v[26:29], v[144:147], v[126:129], v[26:29]
	v_mfma_f32_16x16x32_bf16 v[22:25], v[148:151], v[126:129], v[22:25]
	v_mfma_f32_16x16x32_bf16 v[18:21], v[152:155], v[126:129], v[18:21]
	s_waitcnt lgkmcnt(0)
	v_mfma_f32_16x16x32_bf16 v[14:17], v[134:137], v[156:159], v[14:17]
	v_mfma_f32_16x16x32_bf16 v[10:13], v[144:147], v[156:159], v[10:13]
	v_mfma_f32_16x16x32_bf16 v[6:9], v[148:151], v[156:159], v[6:9]
	v_mfma_f32_16x16x32_bf16 v[2:5], v[152:155], v[156:159], v[2:5]
	s_waitcnt vmcnt(0)
	v_lshl_or_b32 v190, v142, 6, s22
	s_movk_i32 s2, 0x981
	v_cmp_gt_i32_e32 vcc, s2, v190
	s_barrier
; DI bf16_t f2bf(float x) { return (bf16_t)(pack2(x, 0.f) & 0xffffu); }
; DI void phase_win(char* smem, const Params& p, int layer) {
;     ...
;   auto ep = [&](int row, int cbw, int q4, const f32x4& c0, const f32x4& c1, const f32x4& c2, const f32x4& c3) {
;     if (cbw > 2432) return;
;     const int b = row / TT, t = row - b * TT;
;     const bool lat = t >= CTXL;
;     const int pos = t - CTXL;
;     float v[16] = {c0[0], c0[1], c0[2], c0[3], c1[0], c1[1], c1[2], c1[3], c2[0], c2[1], c2[2], c2[3], c3[0], c3[1], c3[2], c3[3]};
;     if (cbw >= 640 && cbw < 768) {
;       bf16_t* vp = p.VsT + ((size_t)(b * 2 + ((cbw - 640) >> 6)) * 64 + q4 * 16) * TT + t;
; #pragma unroll
;       for (int i = 0; i < 16; ++i) vp[(size_t)i * TT] = f2bf(v[i]);
;       return;
;     }
;     const bool r16 = cbw >= 256 && cbw < 640, rkr = cbw == 2432;
;     if (rkr && q4 >= 2) return;
;     if (lat && (r16 || rkr)) {
;       const int a = r16 ? (q4 >> 1) : q4;
;       const int pa = a ? (pos & 63) : (pos >> 6);
;       const float* tab = r16 ? p.ropeS + 2 * (pa * 16 + (q4 & 1) * 8) : p.ropeM + 2 * (pa * 8);
; #pragma unroll
;       for (int k = 0; k < 4; ++k) {
;         const float4 cs = *(const float4*)(tab + 4 * k);
;         const float x0 = v[4 * k], x1 = v[4 * k + 1], x2 = v[4 * k + 2], x3 = v[4 * k + 3];
;         v[4 * k] = x0 * cs.x - x1 * cs.y; v[4 * k + 1] = x1 * cs.x + x0 * cs.y;
;         v[4 * k + 2] = x2 * cs.z - x3 * cs.w; v[4 * k + 3] = x3 * cs.z + x2 * cs.w;
;       }
;     }
	s_and_saveexec_b64 s[96:97], vcc
	s_cbranch_execz .LBB0_557
	v_or_b32_e32 v126, s4, v162
	v_lshl_add_u32 v136, v141, 7, v126
	v_and_b32_e32 v126, 0xffffff80, v190
	s_movk_i32 s2, 0x280
	v_cmp_ne_u32_e64 s[16:17], s2, v126
	s_movk_i32 s2, 0x27f
	v_cmp_lt_i32_e64 s[4:5], s2, v190
	s_movk_i32 s2, 0x980
	v_cmp_ne_u32_e64 s[8:9], s2, v190
	v_cmp_gt_u32_e64 s[6:7], 2, v140
	v_add_u32_e32 v126, 0xffffff00, v190
	v_cmp_eq_u32_e32 vcc, s2, v190
	s_or_b64 s[2:3], s[8:9], s[6:7]
	s_movk_i32 s6, 0x180
	v_cmp_gt_u32_e64 s[12:13], s6, v126
	s_or_b64 s[86:87], vcc, s[12:13]
	v_lshrrev_b32_e32 v160, 6, v126
	v_cndmask_b32_e64 v127, 0, 1, s[12:13]
	v_lshrrev_b32_e32 v127, v127, v140
	v_cmp_eq_u32_e64 s[14:15], 0, v127
	v_add_u32_e32 v127, 0xfffffe00, v190
	v_mul_hi_i32 v126, v136, s1
	s_cmp_eq_u32 s10, 1
	v_lshrrev_b32_e32 v159, 6, v127
	v_lshrrev_b32_e32 v127, 31, v126
	v_ashrrev_i32_e32 v126, 11, v126
	v_lshlrev_b32_e32 v158, 4, v140
	s_movk_i32 s6, 0x1ff
	s_cselect_b64 s[94:95], -1, 0
	s_movk_i32 s10, 0xff
	s_cmpk_gt_u32 s22, 0x7ff
	v_add_u32_e32 v139, v126, v127
	v_and_b32_e32 v161, 16, v158
	v_cmp_lt_i32_e64 s[6:7], s6, v190
	v_cmp_lt_i32_e64 s[10:11], s10, v190
	s_cselect_b64 s[22:23], -1, 0
	v_ashrrev_i32_e32 v135, 31, v190
	v_mov_b32_e32 v134, v190
	v_mad_i32_i24 v138, v139, s80, v136
	s_and_saveexec_b64 s[30:31], s[16:17]
	s_xor_b64 s[30:31], exec, s[30:31]
	s_cbranch_execz .LBB0_594
	s_and_saveexec_b64 s[52:53], s[2:3]
	s_cbranch_execz .LBB0_593
	s_movk_i32 s45, 0xff
	v_cmp_lt_i32_e32 vcc, s45, v138
	s_and_b64 s[46:47], s[86:87], vcc
	v_mov_b32_e32 v140, v131
	v_mov_b32_e32 v141, v133
	v_mov_b32_e32 v142, v123
	v_mov_b32_e32 v143, v125
	v_mov_b32_e32 v144, v119
	v_mov_b32_e32 v145, v121
	v_mov_b32_e32 v154, v115
	v_mov_b32_e32 v155, v117
	v_mov_b32_e32 v146, v130
	v_mov_b32_e32 v147, v132
	v_mov_b32_e32 v148, v122
	v_mov_b32_e32 v149, v124
	v_mov_b32_e32 v150, v118
	v_mov_b32_e32 v151, v120
	v_mov_b32_e32 v152, v114
	v_mov_b32_e32 v153, v116
	s_and_saveexec_b64 s[54:55], s[46:47]
	s_cbranch_execz .LBB0_571
	v_readlane_b32 s46, v252, 1
	v_cndmask_b32_e64 v128, v238, v240, s[12:13]
	v_mov_b32_e32 v129, v191
	v_readlane_b32 s47, v252, 2
	v_add_u32_e32 v126, 0xffffff00, v138
	v_lshrrev_b32_e32 v126, 6, v126
	v_lshl_add_u64 v[128:129], s[46:47], 0, v[128:129]
	global_load_dwordx2 v[128:129], v[128:129], off
	v_cndmask_b32_e64 v126, v162, v126, s[14:15]
	v_lshlrev_b32_e32 v127, 4, v126
	v_lshl_or_b32 v126, v126, 5, v161
	v_cndmask_b32_e64 v126, v127, v126, s[12:13]
	v_mov_b32_e32 v127, v191
	v_mov_b32_e32 v182, v130
	v_mov_b32_e32 v183, v133
	v_mov_b32_e32 v130, v131
	v_mov_b32_e32 v131, v132
	s_waitcnt vmcnt(0)
	v_lshl_add_u64 v[156:157], v[126:127], 2, v[128:129]
	global_load_dwordx4 v[126:129], v[156:157], off offset:48
	global_load_dwordx4 v[164:167], v[156:157], off offset:32
	global_load_dwordx4 v[168:171], v[156:157], off offset:16
	global_load_dwordx4 v[172:175], v[156:157], off
	s_waitcnt vmcnt(3)
	v_mov_b32_e32 v156, v127
	s_waitcnt vmcnt(2)
	v_mov_b32_e32 v180, v165
	s_waitcnt vmcnt(1)
	v_mov_b32_e32 v178, v169
	s_waitcnt vmcnt(0)
	v_mov_b32_e32 v132, v172
	v_mov_b32_e32 v133, v175
	v_mov_b32_e32 v176, v173
	v_mov_b32_e32 v177, v174
	v_pk_mul_f32 v[130:131], v[130:131], v[132:133]
	v_mov_b32_e32 v132, v173
	v_pk_mul_f32 v[132:133], v[140:141], v[132:133]
	v_pk_fma_f32 v[140:141], v[182:183], v[176:177], v[130:131]
	v_mov_b32_e32 v130, v122
	v_mov_b32_e32 v131, v125
	v_mov_b32_e32 v122, v123
	v_mov_b32_e32 v123, v124
	v_mov_b32_e32 v124, v168
	v_mov_b32_e32 v125, v171
	v_mov_b32_e32 v179, v170
	v_pk_mul_f32 v[122:123], v[122:123], v[124:125]
	v_mov_b32_e32 v124, v169
	v_pk_mul_f32 v[124:125], v[142:143], v[124:125]
	v_pk_fma_f32 v[142:143], v[130:131], v[178:179], v[122:123]
	v_mov_b32_e32 v122, v118
	v_mov_b32_e32 v123, v121
	v_mov_b32_e32 v118, v119
	v_mov_b32_e32 v119, v120
	v_mov_b32_e32 v120, v164
	v_mov_b32_e32 v121, v167
	v_mov_b32_e32 v181, v166
	v_pk_mul_f32 v[118:119], v[118:119], v[120:121]
	v_mov_b32_e32 v120, v165
	v_pk_mul_f32 v[120:121], v[144:145], v[120:121]
	v_pk_fma_f32 v[144:145], v[122:123], v[180:181], v[118:119]
	v_mov_b32_e32 v118, v114
	v_mov_b32_e32 v119, v117
	v_mov_b32_e32 v114, v115
	v_mov_b32_e32 v115, v116
	v_mov_b32_e32 v116, v126
	v_mov_b32_e32 v117, v129
	v_pk_mul_f32 v[114:115], v[114:115], v[116:117]
	v_mov_b32_e32 v116, v127
	v_mov_b32_e32 v157, v128
	v_mov_b32_e32 v173, v174
	v_mov_b32_e32 v169, v170
	v_mov_b32_e32 v165, v166
	v_pk_mul_f32 v[116:117], v[154:155], v[116:117]
	v_mov_b32_e32 v127, v128
	v_pk_fma_f32 v[146:147], v[146:147], v[172:173], v[132:133] neg_lo:[0,0,1] neg_hi:[0,0,1]
	v_pk_fma_f32 v[148:149], v[148:149], v[168:169], v[124:125] neg_lo:[0,0,1] neg_hi:[0,0,1]
	v_pk_fma_f32 v[150:151], v[150:151], v[164:165], v[120:121] neg_lo:[0,0,1] neg_hi:[0,0,1]
	v_pk_fma_f32 v[152:153], v[152:153], v[126:127], v[116:117] neg_lo:[0,0,1] neg_hi:[0,0,1]
	v_pk_fma_f32 v[154:155], v[118:119], v[156:157], v[114:115]
